# rowscale epilogues (SwiGLU, even/odd in-proj): 16 ssp loads per tile hoisted into one burst, reduction chains renamed into slot VGPRs
# speedup vs baseline: 1.1615x; 1.0030x over previous
; DI float sigmoidf_(float x) { return frcp(1.f + __expf(-x)); }
; DI void st_bf16x4(bf16_t* p, f32x4 v) { u32x2 o; o.x = pk2e(v[0], v[1]); o.y = pk2e(v[2], v[3]); *(u32x2*)p = o; }
;   DI float operator()(int row, int colbase, int fq, f32x4 v0, f32x4 v1) const { one(row, colbase + 4 * fq, v0); one(row, colbase + 16 + 4 * fq, v1); return 0.f; }
;   DI float operator()(int row, int colbase, int fq, f32x4 v0, f32x4 v1) const { one(row, colbase + 4 * fq, v0); one(row, colbase + 16 + 4 * fq, v1); return 0.f; }
;   DI float operator()(int row, int colbase, int fq, f32x4 v0, f32x4 v1) const { one(row, colbase + 4 * fq, v0); one(row, colbase + 16 + 4 * fq, v1); return 0.f; }
;   DI float operator()(int row, int colbase, int fq, f32x4 v0, f32x4 v1) const { one(row, colbase + 4 * fq, v0); one(row, colbase + 16 + 4 * fq, v1); return 0.f; }
;     ...
;       for (int m = 0; m < 4; ++m) {
;         const int row = brow + ai * HALF + wr * 64 + m * 16 + fr_e;
;         const float rsc = epi.rowscale(row);
;         float ssq = 0.f;
; #pragma unroll
;         for (int bj = 0; bj < 2; ++bj)
;           ssq += epi(row, bcol + bj * HALF + wc * 32, fq_e, acc[ai][bj][m][0] * rsc, acc[ai][bj][m][1] * rsc);
;         rowss[ai][m] = ssq;
;         __builtin_amdgcn_sched_barrier(0);
;       }
;   DI float rowscale(int row) const { const f32x4 a = *(const f32x4*)(ssp_in + (size_t)row * 8), b = *(const f32x4*)(ssp_in + (size_t)row * 8 + 4);
;     return rsqrtf((((a[0] + a[1]) + (a[2] + a[3])) + ((b[0] + b[1]) + (b[2] + b[3]))) * (1.f / D_) + EPS_); }
;   DI float operator()(int row, int colbase, int fq, f32x4 v0, f32x4 v1) const {
;     f32x4 r;
; #pragma unroll
;     for (int e = 0; e < 4; ++e) r[e] = v0[e] * sigmoidf_(v0[e]) * v1[e];
;     st_bf16x4(hid + (size_t)row * FFN_ + (colbase >> 1) + 4 * fq, r); return 0.f;
;   }
.LBB0_21:
	v_mov_b32_e32 v0, v199
	s_add_i32 s10, s10, s24
	s_mov_b32 s14, 0x800000
	v_and_or_b32 v136, v0, 15, s10
	v_ashrrev_i32_e32 v137, 31, v136
	v_lshlrev_b64 v[138:139], 5, v[136:137]
	v_lshl_add_u64 v[138:139], s[4:5], 0, v[138:139]
	s_mov_b64 s[100:101], 0x1000
	v_lshl_add_u64 v[240:241], v[138:139], 0, s[100:101]
	global_load_dwordx4 v[162:165], v[240:241], off offset:-4096
	global_load_dwordx4 v[166:169], v[240:241], off offset:-4080
	global_load_dwordx4 v[170:173], v[240:241], off offset:-3584
	global_load_dwordx4 v[174:177], v[240:241], off offset:-3568
	global_load_dwordx4 v[178:181], v[240:241], off offset:-3072
	global_load_dwordx4 v[182:185], v[240:241], off offset:-3056
	global_load_dwordx4 v[200:203], v[240:241], off offset:-2560
	global_load_dwordx4 v[204:207], v[240:241], off offset:-2544
	global_load_dwordx4 v[208:211], v[240:241], off
	global_load_dwordx4 v[212:215], v[240:241], off offset:16
	global_load_dwordx4 v[216:219], v[240:241], off offset:512
	global_load_dwordx4 v[220:223], v[240:241], off offset:528
	global_load_dwordx4 v[224:227], v[240:241], off offset:1024
	global_load_dwordx4 v[228:231], v[240:241], off offset:1040
	global_load_dwordx4 v[232:235], v[240:241], off offset:1536
	global_load_dwordx4 v[236:239], v[240:241], off offset:1552
	v_lshrrev_b32_e32 v0, 1, v0
	v_and_b32_e32 v0, 24, v0
	v_lshl_add_u64 v[134:135], s[0:1], 0, v[0:1]
	s_or_b32 s10, s12, s25
	s_ashr_i32 s10, s10, 1
	s_movk_i32 s15, 0x2c00
	s_ashr_i32 s11, s10, 31
	s_lshl_b64 s[10:11], s[10:11], 1
	s_waitcnt vmcnt(14)
	v_mov_b32_e32 v138, v162
	v_mov_b32_e32 v139, v166
	v_mov_b32_e32 v166, v163
	v_mov_b32_e32 v162, v164
	v_mov_b32_e32 v163, v168
	v_mov_b32_e32 v168, v165
	v_pk_add_f32 v[138:139], v[138:139], v[166:167]
	v_pk_add_f32 v[162:163], v[162:163], v[168:169]
	s_nop 0
	v_pk_add_f32 v[138:139], v[138:139], v[162:163]
	s_nop 0
	v_add_f32_e32 v0, v138, v139
	v_fmamk_f32 v0, v0, 0x3a000000, v249
	v_cmp_gt_f32_e32 vcc, s14, v0
	v_mul_f32_e32 v137, 0x4b800000, v0
	v_mad_i64_i32 v[138:139], s[12:13], v136, s15, v[134:135]
	v_cndmask_b32_e32 v0, v0, v137, vcc
	v_rsq_f32_e32 v0, v0
	s_nop 0
	v_mul_f32_e32 v137, 0x45800000, v0
	v_cndmask_b32_e32 v0, v0, v137, vcc
	v_pk_mul_f32 v[122:123], v[122:123], v[0:1] op_sel_hi:[1,0]
	v_pk_mul_f32 v[124:125], v[124:125], v[0:1] op_sel_hi:[1,0]
	v_mul_f32_e32 v137, 0xbfb8aa3b, v122
	v_exp_f32_e32 v137, v137
	v_pk_mul_f32 v[126:127], v[126:127], v[0:1] op_sel_hi:[1,0]
	v_pk_mul_f32 v[118:119], v[118:119], v[0:1] op_sel_hi:[1,0]
	v_pk_mul_f32 v[128:129], v[128:129], v[0:1] op_sel_hi:[1,0]
	v_add_f32_e32 v137, 1.0, v137
	v_rcp_f32_e32 v142, v137
	v_mul_f32_e32 v137, 0xbfb8aa3b, v123
	v_exp_f32_e32 v137, v137
	v_pk_mul_f32 v[120:121], v[120:121], v[0:1] op_sel_hi:[1,0]
	v_pk_mul_f32 v[116:117], v[116:117], v[0:1] op_sel_hi:[1,0]
	v_pk_mul_f32 v[114:115], v[114:115], v[0:1] op_sel_hi:[1,0]
	v_add_f32_e32 v137, 1.0, v137
	v_rcp_f32_e32 v143, v137
	v_mul_f32_e32 v0, 0xbfb8aa3b, v118
	v_exp_f32_e32 v0, v0
	v_pk_mul_f32 v[122:123], v[122:123], v[142:143]
	s_nop 0
	v_pk_mul_f32 v[122:123], v[126:127], v[122:123]
	v_mul_f32_e32 v126, 0xbfb8aa3b, v124
	v_mul_f32_e32 v127, 0xbfb8aa3b, v125
	v_exp_f32_e32 v126, v126
	v_exp_f32_e32 v127, v127
	v_cvt_pk_bf16_f32 v122, v122, v123
	v_add_f32_e32 v0, 1.0, v0
	v_add_f32_e32 v126, 1.0, v126
	v_add_f32_e32 v127, 1.0, v127
	v_rcp_f32_e32 v126, v126
	v_rcp_f32_e32 v127, v127
	s_nop 0
	v_pk_mul_f32 v[124:125], v[124:125], v[126:127]
	s_nop 0
	v_pk_mul_f32 v[124:125], v[128:129], v[124:125]
	v_lshl_add_u64 v[126:127], v[138:139], 0, s[10:11]
	v_cvt_pk_bf16_f32 v123, v124, v125
	global_store_dwordx2 v[126:127], v[122:123], off
	v_rcp_f32_e32 v122, v0
	v_mul_f32_e32 v0, 0xbfb8aa3b, v119
	v_exp_f32_e32 v0, v0
	s_nop 0
	v_add_f32_e32 v0, 1.0, v0
	v_rcp_f32_e32 v123, v0
	v_mul_f32_e32 v0, 0xbfb8aa3b, v120
	v_exp_f32_e32 v0, v0
	v_pk_mul_f32 v[118:119], v[118:119], v[122:123]
	s_nop 0
	v_pk_mul_f32 v[114:115], v[114:115], v[118:119]
	v_add_f32_e32 v0, 1.0, v0
	v_rcp_f32_e32 v118, v0
	v_mul_f32_e32 v0, 0xbfb8aa3b, v121
	v_exp_f32_e32 v0, v0
	v_cvt_pk_bf16_f32 v114, v114, v115
	v_add_f32_e32 v0, 1.0, v0
	v_rcp_f32_e32 v119, v0
	s_nop 0
	v_pk_mul_f32 v[118:119], v[120:121], v[118:119]
	s_nop 0
	v_pk_mul_f32 v[116:117], v[116:117], v[118:119]
	s_nop 0
	v_cvt_pk_bf16_f32 v115, v116, v117
	global_store_dwordx2 v[126:127], v[114:115], off offset:128
	v_or_b32_e32 v122, 16, v136
	v_ashrrev_i32_e32 v123, 31, v122
	v_lshlrev_b64 v[114:115], 5, v[122:123]
	v_lshl_add_u64 v[118:119], s[4:5], 0, v[114:115]
	s_nop 0
	s_waitcnt vmcnt(12)
; DI float sigmoidf_(float x) { return frcp(1.f + __expf(-x)); }
; DI void st_bf16x4(bf16_t* p, f32x4 v) { u32x2 o; o.x = pk2e(v[0], v[1]); o.y = pk2e(v[2], v[3]); *(u32x2*)p = o; }
;   DI float operator()(int row, int colbase, int fq, f32x4 v0, f32x4 v1) const { one(row, colbase + 4 * fq, v0); one(row, colbase + 16 + 4 * fq, v1); return 0.f; }
;   DI float operator()(int row, int colbase, int fq, f32x4 v0, f32x4 v1) const { one(row, colbase + 4 * fq, v0); one(row, colbase + 16 + 4 * fq, v1); return 0.f; }
;   DI float operator()(int row, int colbase, int fq, f32x4 v0, f32x4 v1) const { one(row, colbase + 4 * fq, v0); one(row, colbase + 16 + 4 * fq, v1); return 0.f; }
;   DI float operator()(int row, int colbase, int fq, f32x4 v0, f32x4 v1) const { one(row, colbase + 4 * fq, v0); one(row, colbase + 16 + 4 * fq, v1); return 0.f; }
;     ...
;       for (int m = 0; m < 4; ++m) {
;         const int row = brow + ai * HALF + wr * 64 + m * 16 + fr_e;
;         const float rsc = epi.rowscale(row);
;         float ssq = 0.f;
; #pragma unroll
;         for (int bj = 0; bj < 2; ++bj)
;           ssq += epi(row, bcol + bj * HALF + wc * 32, fq_e, acc[ai][bj][m][0] * rsc, acc[ai][bj][m][1] * rsc);
;   DI float rowscale(int row) const { const f32x4 a = *(const f32x4*)(ssp_in + (size_t)row * 8), b = *(const f32x4*)(ssp_in + (size_t)row * 8 + 4);
;     return rsqrtf((((a[0] + a[1]) + (a[2] + a[3])) + ((b[0] + b[1]) + (b[2] + b[3]))) * (1.f / D_) + EPS_); }
;   DI float operator()(int row, int colbase, int fq, f32x4 v0, f32x4 v1) const {
;     f32x4 r;
; #pragma unroll
;     for (int e = 0; e < 4; ++e) r[e] = v0[e] * sigmoidf_(v0[e]) * v1[e];
;     st_bf16x4(hid + (size_t)row * FFN_ + (colbase >> 1) + 4 * fq, r); return 0.f;
	v_mov_b32_e32 v124, v170
	v_mov_b32_e32 v125, v174
	v_mov_b32_e32 v174, v171
	v_pk_add_f32 v[170:171], v[124:125], v[174:175]
	v_mov_b32_e32 v174, v172
	v_mov_b32_e32 v175, v176
	v_mov_b32_e32 v176, v173
	v_pk_add_f32 v[172:173], v[174:175], v[176:177]
	s_nop 0
	v_pk_add_f32 v[170:171], v[170:171], v[172:173]
	s_nop 0
	v_add_f32_e32 v0, v170, v171
	v_fmamk_f32 v0, v0, 0x3a000000, v249
	v_cmp_gt_f32_e32 vcc, s14, v0
	v_mul_f32_e32 v114, 0x4b800000, v0
	s_nop 0
	v_cndmask_b32_e32 v0, v0, v114, vcc
	v_rsq_f32_e32 v0, v0
	s_nop 0
	v_mul_f32_e32 v114, 0x45800000, v0
	v_cndmask_b32_e32 v0, v0, v114, vcc
	v_pk_mul_f32 v[106:107], v[106:107], v[0:1] op_sel_hi:[1,0]
	v_pk_mul_f32 v[108:109], v[108:109], v[0:1] op_sel_hi:[1,0]
	v_mul_f32_e32 v116, 0xbfb8aa3b, v106
	v_mul_f32_e32 v117, 0xbfb8aa3b, v107
	v_exp_f32_e32 v116, v116
	v_exp_f32_e32 v117, v117
	v_pk_mul_f32 v[110:111], v[110:111], v[0:1] op_sel_hi:[1,0]
	v_pk_mul_f32 v[102:103], v[102:103], v[0:1] op_sel_hi:[1,0]
	v_add_f32_e32 v116, 1.0, v116
	v_add_f32_e32 v117, 1.0, v117
	v_rcp_f32_e32 v116, v116
	v_rcp_f32_e32 v117, v117
	v_pk_mul_f32 v[112:113], v[112:113], v[0:1] op_sel_hi:[1,0]
	v_pk_mul_f32 v[104:105], v[104:105], v[0:1] op_sel_hi:[1,0]
	v_pk_mul_f32 v[100:101], v[100:101], v[0:1] op_sel_hi:[1,0]
	v_pk_mul_f32 v[106:107], v[106:107], v[116:117]
	v_pk_mul_f32 v[98:99], v[98:99], v[0:1] op_sel_hi:[1,0]
	v_pk_mul_f32 v[110:111], v[110:111], v[106:107]
	v_mul_f32_e32 v106, 0xbfb8aa3b, v108
	v_mul_f32_e32 v107, 0xbfb8aa3b, v109
	v_exp_f32_e32 v106, v106
	v_exp_f32_e32 v107, v107
	v_mul_f32_e32 v0, 0xbfb8aa3b, v102
	v_exp_f32_e32 v0, v0
	v_add_f32_e32 v106, 1.0, v106
	v_add_f32_e32 v107, 1.0, v107
	v_rcp_f32_e32 v106, v106
	v_rcp_f32_e32 v107, v107
	v_add_f32_e32 v0, 1.0, v0
	v_cvt_pk_bf16_f32 v110, v110, v111
	v_mad_i64_i32 v[114:115], s[12:13], v122, s15, v[134:135]
	v_pk_mul_f32 v[106:107], v[108:109], v[106:107]
	s_nop 0
	v_pk_mul_f32 v[108:109], v[112:113], v[106:107]
	v_lshl_add_u64 v[106:107], v[114:115], 0, s[10:11]
	v_cvt_pk_bf16_f32 v111, v108, v109
	v_rcp_f32_e32 v108, v0
	v_mul_f32_e32 v0, 0xbfb8aa3b, v103
	v_exp_f32_e32 v0, v0
	global_store_dwordx2 v[106:107], v[110:111], off
	v_add_f32_e32 v0, 1.0, v0
	v_rcp_f32_e32 v109, v0
	v_mul_f32_e32 v0, 0xbfb8aa3b, v104
	v_exp_f32_e32 v0, v0
	v_pk_mul_f32 v[102:103], v[102:103], v[108:109]
	s_nop 0
	v_pk_mul_f32 v[98:99], v[98:99], v[102:103]
	v_add_f32_e32 v0, 1.0, v0
	v_rcp_f32_e32 v102, v0
	v_mul_f32_e32 v0, 0xbfb8aa3b, v105
	v_exp_f32_e32 v0, v0
	v_cvt_pk_bf16_f32 v98, v98, v99
	v_add_f32_e32 v0, 1.0, v0
	v_rcp_f32_e32 v103, v0
	s_nop 0
	v_pk_mul_f32 v[102:103], v[104:105], v[102:103]
	s_nop 0
	v_pk_mul_f32 v[100:101], v[100:101], v[102:103]
	s_nop 0
	v_cvt_pk_bf16_f32 v99, v100, v101
	global_store_dwordx2 v[106:107], v[98:99], off offset:128
	v_or_b32_e32 v106, 32, v136
	v_ashrrev_i32_e32 v107, 31, v106
	v_lshlrev_b64 v[98:99], 5, v[106:107]
	v_lshl_add_u64 v[102:103], s[4:5], 0, v[98:99]
	s_nop 0
	s_waitcnt vmcnt(10)
	v_mov_b32_e32 v108, v178
	v_mov_b32_e32 v109, v182
	v_mov_b32_e32 v182, v179
	v_pk_add_f32 v[178:179], v[108:109], v[182:183]
	v_mov_b32_e32 v182, v180
	v_mov_b32_e32 v183, v184
	v_mov_b32_e32 v184, v181
	v_pk_add_f32 v[180:181], v[182:183], v[184:185]
	s_nop 0
	v_pk_add_f32 v[178:179], v[178:179], v[180:181]
	s_nop 0
	v_add_f32_e32 v0, v178, v179
	v_fmamk_f32 v0, v0, 0x3a000000, v249
	v_cmp_gt_f32_e32 vcc, s14, v0
	v_mul_f32_e32 v98, 0x4b800000, v0
	s_nop 0
	v_cndmask_b32_e32 v0, v0, v98, vcc
	v_rsq_f32_e32 v0, v0
	s_nop 0
	v_mul_f32_e32 v98, 0x45800000, v0
	v_cndmask_b32_e32 v0, v0, v98, vcc
	v_pk_mul_f32 v[90:91], v[90:91], v[0:1] op_sel_hi:[1,0]
	v_pk_mul_f32 v[92:93], v[92:93], v[0:1] op_sel_hi:[1,0]
	v_mul_f32_e32 v100, 0xbfb8aa3b, v90
	v_mul_f32_e32 v101, 0xbfb8aa3b, v91
	v_exp_f32_e32 v100, v100
	v_exp_f32_e32 v101, v101
	v_pk_mul_f32 v[94:95], v[94:95], v[0:1] op_sel_hi:[1,0]
	v_pk_mul_f32 v[86:87], v[86:87], v[0:1] op_sel_hi:[1,0]
	v_add_f32_e32 v100, 1.0, v100
	v_add_f32_e32 v101, 1.0, v101
	v_rcp_f32_e32 v100, v100
	v_rcp_f32_e32 v101, v101
	v_pk_mul_f32 v[96:97], v[96:97], v[0:1] op_sel_hi:[1,0]
	v_pk_mul_f32 v[88:89], v[88:89], v[0:1] op_sel_hi:[1,0]
	v_pk_mul_f32 v[84:85], v[84:85], v[0:1] op_sel_hi:[1,0]
	v_pk_mul_f32 v[90:91], v[90:91], v[100:101]
	v_pk_mul_f32 v[82:83], v[82:83], v[0:1] op_sel_hi:[1,0]
	v_pk_mul_f32 v[94:95], v[94:95], v[90:91]
	v_mul_f32_e32 v90, 0xbfb8aa3b, v92
	v_mul_f32_e32 v91, 0xbfb8aa3b, v93
	v_exp_f32_e32 v90, v90
	v_exp_f32_e32 v91, v91
	v_mul_f32_e32 v0, 0xbfb8aa3b, v86
	v_exp_f32_e32 v0, v0
	v_add_f32_e32 v90, 1.0, v90
	v_add_f32_e32 v91, 1.0, v91
	v_rcp_f32_e32 v90, v90
	v_rcp_f32_e32 v91, v91
	v_add_f32_e32 v0, 1.0, v0
	v_cvt_pk_bf16_f32 v94, v94, v95
	v_mad_i64_i32 v[98:99], s[12:13], v106, s15, v[134:135]
	v_pk_mul_f32 v[90:91], v[92:93], v[90:91]
	s_nop 0
	v_pk_mul_f32 v[92:93], v[96:97], v[90:91]
	v_lshl_add_u64 v[90:91], v[98:99], 0, s[10:11]
	v_cvt_pk_bf16_f32 v95, v92, v93
	v_rcp_f32_e32 v92, v0
	v_mul_f32_e32 v0, 0xbfb8aa3b, v87
	v_exp_f32_e32 v0, v0
	global_store_dwordx2 v[90:91], v[94:95], off
	v_add_f32_e32 v0, 1.0, v0
	v_rcp_f32_e32 v93, v0
	v_mul_f32_e32 v0, 0xbfb8aa3b, v88
	v_exp_f32_e32 v0, v0
	v_pk_mul_f32 v[86:87], v[86:87], v[92:93]
	s_nop 0
	v_pk_mul_f32 v[82:83], v[82:83], v[86:87]
	v_add_f32_e32 v0, 1.0, v0
	v_rcp_f32_e32 v86, v0
	v_mul_f32_e32 v0, 0xbfb8aa3b, v89
	v_exp_f32_e32 v0, v0
	v_cvt_pk_bf16_f32 v82, v82, v83
	v_add_f32_e32 v0, 1.0, v0
	v_rcp_f32_e32 v87, v0
	s_nop 0
	v_pk_mul_f32 v[86:87], v[88:89], v[86:87]
	s_nop 0
	v_pk_mul_f32 v[84:85], v[84:85], v[86:87]
	s_nop 0
	v_cvt_pk_bf16_f32 v83, v84, v85
	global_store_dwordx2 v[90:91], v[82:83], off offset:128
	v_or_b32_e32 v90, 48, v136
	v_ashrrev_i32_e32 v91, 31, v90
	v_lshlrev_b64 v[82:83], 5, v[90:91]
	v_lshl_add_u64 v[86:87], s[4:5], 0, v[82:83]
	s_nop 0
	s_waitcnt vmcnt(8)
; DI float sigmoidf_(float x) { return frcp(1.f + __expf(-x)); }
; DI void st_bf16x4(bf16_t* p, f32x4 v) { u32x2 o; o.x = pk2e(v[0], v[1]); o.y = pk2e(v[2], v[3]); *(u32x2*)p = o; }
;   DI float operator()(int row, int colbase, int fq, f32x4 v0, f32x4 v1) const { one(row, colbase + 4 * fq, v0); one(row, colbase + 16 + 4 * fq, v1); return 0.f; }
;   DI float operator()(int row, int colbase, int fq, f32x4 v0, f32x4 v1) const { one(row, colbase + 4 * fq, v0); one(row, colbase + 16 + 4 * fq, v1); return 0.f; }
;   DI float operator()(int row, int colbase, int fq, f32x4 v0, f32x4 v1) const { one(row, colbase + 4 * fq, v0); one(row, colbase + 16 + 4 * fq, v1); return 0.f; }
;   DI float operator()(int row, int colbase, int fq, f32x4 v0, f32x4 v1) const { one(row, colbase + 4 * fq, v0); one(row, colbase + 16 + 4 * fq, v1); return 0.f; }
;     ...
;       for (int m = 0; m < 4; ++m) {
;         const int row = brow + ai * HALF + wr * 64 + m * 16 + fr_e;
;         const float rsc = epi.rowscale(row);
;         float ssq = 0.f;
; #pragma unroll
;         for (int bj = 0; bj < 2; ++bj)
;           ssq += epi(row, bcol + bj * HALF + wc * 32, fq_e, acc[ai][bj][m][0] * rsc, acc[ai][bj][m][1] * rsc);
;   DI float rowscale(int row) const { const f32x4 a = *(const f32x4*)(ssp_in + (size_t)row * 8), b = *(const f32x4*)(ssp_in + (size_t)row * 8 + 4);
;     return rsqrtf((((a[0] + a[1]) + (a[2] + a[3])) + ((b[0] + b[1]) + (b[2] + b[3]))) * (1.f / D_) + EPS_); }
;   DI float operator()(int row, int colbase, int fq, f32x4 v0, f32x4 v1) const {
;     f32x4 r;
; #pragma unroll
;     for (int e = 0; e < 4; ++e) r[e] = v0[e] * sigmoidf_(v0[e]) * v1[e];
;     st_bf16x4(hid + (size_t)row * FFN_ + (colbase >> 1) + 4 * fq, r); return 0.f;
	v_mov_b32_e32 v92, v200
	v_mov_b32_e32 v93, v204
	v_mov_b32_e32 v204, v201
	v_pk_add_f32 v[200:201], v[92:93], v[204:205]
	v_mov_b32_e32 v204, v202
	v_mov_b32_e32 v205, v206
	v_mov_b32_e32 v206, v203
	v_pk_add_f32 v[202:203], v[204:205], v[206:207]
	s_nop 0
	v_pk_add_f32 v[200:201], v[200:201], v[202:203]
	s_nop 0
	v_add_f32_e32 v0, v200, v201
	v_fmamk_f32 v0, v0, 0x3a000000, v249
	v_cmp_gt_f32_e32 vcc, s14, v0
	v_mul_f32_e32 v82, 0x4b800000, v0
	s_nop 0
	v_cndmask_b32_e32 v0, v0, v82, vcc
	v_rsq_f32_e32 v0, v0
	s_nop 0
	v_mul_f32_e32 v82, 0x45800000, v0
	v_cndmask_b32_e32 v0, v0, v82, vcc
	v_pk_mul_f32 v[74:75], v[74:75], v[0:1] op_sel_hi:[1,0]
	v_pk_mul_f32 v[76:77], v[76:77], v[0:1] op_sel_hi:[1,0]
	v_mul_f32_e32 v84, 0xbfb8aa3b, v74
	v_mul_f32_e32 v85, 0xbfb8aa3b, v75
	v_exp_f32_e32 v84, v84
	v_exp_f32_e32 v85, v85
	v_pk_mul_f32 v[78:79], v[78:79], v[0:1] op_sel_hi:[1,0]
	v_pk_mul_f32 v[70:71], v[70:71], v[0:1] op_sel_hi:[1,0]
	v_add_f32_e32 v84, 1.0, v84
	v_add_f32_e32 v85, 1.0, v85
	v_rcp_f32_e32 v84, v84
	v_rcp_f32_e32 v85, v85
	v_pk_mul_f32 v[80:81], v[80:81], v[0:1] op_sel_hi:[1,0]
	v_pk_mul_f32 v[72:73], v[72:73], v[0:1] op_sel_hi:[1,0]
	v_pk_mul_f32 v[68:69], v[68:69], v[0:1] op_sel_hi:[1,0]
	v_pk_mul_f32 v[74:75], v[74:75], v[84:85]
	v_pk_mul_f32 v[66:67], v[66:67], v[0:1] op_sel_hi:[1,0]
	v_pk_mul_f32 v[78:79], v[78:79], v[74:75]
	v_mul_f32_e32 v74, 0xbfb8aa3b, v76
	v_mul_f32_e32 v75, 0xbfb8aa3b, v77
	v_exp_f32_e32 v74, v74
	v_exp_f32_e32 v75, v75
	v_mul_f32_e32 v0, 0xbfb8aa3b, v70
	v_exp_f32_e32 v0, v0
	v_add_f32_e32 v74, 1.0, v74
	v_add_f32_e32 v75, 1.0, v75
	v_rcp_f32_e32 v74, v74
	v_rcp_f32_e32 v75, v75
	v_add_f32_e32 v0, 1.0, v0
	v_cvt_pk_bf16_f32 v78, v78, v79
	v_mad_i64_i32 v[82:83], s[12:13], v90, s15, v[134:135]
	v_pk_mul_f32 v[74:75], v[76:77], v[74:75]
	s_nop 0
	v_pk_mul_f32 v[76:77], v[80:81], v[74:75]
	v_lshl_add_u64 v[74:75], v[82:83], 0, s[10:11]
	v_cvt_pk_bf16_f32 v79, v76, v77
	v_rcp_f32_e32 v76, v0
	v_mul_f32_e32 v0, 0xbfb8aa3b, v71
	v_exp_f32_e32 v0, v0
	global_store_dwordx2 v[74:75], v[78:79], off
	v_add_f32_e32 v0, 1.0, v0
	v_rcp_f32_e32 v77, v0
	v_mul_f32_e32 v0, 0xbfb8aa3b, v72
	v_exp_f32_e32 v0, v0
	v_pk_mul_f32 v[70:71], v[70:71], v[76:77]
	s_nop 0
	v_pk_mul_f32 v[66:67], v[66:67], v[70:71]
	v_add_f32_e32 v0, 1.0, v0
	v_rcp_f32_e32 v70, v0
	v_mul_f32_e32 v0, 0xbfb8aa3b, v73
	v_exp_f32_e32 v0, v0
	v_cvt_pk_bf16_f32 v66, v66, v67
	v_add_f32_e32 v0, 1.0, v0
	v_rcp_f32_e32 v71, v0
	s_nop 0
	v_pk_mul_f32 v[70:71], v[72:73], v[70:71]
	s_nop 0
	v_pk_mul_f32 v[68:69], v[68:69], v[70:71]
	s_nop 0
	v_cvt_pk_bf16_f32 v67, v68, v69
	global_store_dwordx2 v[74:75], v[66:67], off offset:128
	v_add_u32_e32 v74, 0x80, v136
	v_ashrrev_i32_e32 v75, 31, v74
	v_lshlrev_b64 v[66:67], 5, v[74:75]
	v_lshl_add_u64 v[70:71], s[4:5], 0, v[66:67]
	s_nop 0
	s_waitcnt vmcnt(6)
	v_mov_b32_e32 v76, v208
	v_mov_b32_e32 v77, v212
	v_mov_b32_e32 v212, v209
	v_pk_add_f32 v[208:209], v[76:77], v[212:213]
	v_mov_b32_e32 v212, v210
	v_mov_b32_e32 v213, v214
	v_mov_b32_e32 v214, v211
	v_pk_add_f32 v[210:211], v[212:213], v[214:215]
	s_nop 0
	v_pk_add_f32 v[208:209], v[208:209], v[210:211]
	s_nop 0
	v_add_f32_e32 v0, v208, v209
	v_fmamk_f32 v0, v0, 0x3a000000, v249
	v_cmp_gt_f32_e32 vcc, s14, v0
	v_mul_f32_e32 v66, 0x4b800000, v0
	s_nop 0
	v_cndmask_b32_e32 v0, v0, v66, vcc
	v_rsq_f32_e32 v0, v0
	s_nop 0
	v_mul_f32_e32 v66, 0x45800000, v0
	v_cndmask_b32_e32 v0, v0, v66, vcc
	v_pk_mul_f32 v[58:59], v[58:59], v[0:1] op_sel_hi:[1,0]
	v_pk_mul_f32 v[60:61], v[60:61], v[0:1] op_sel_hi:[1,0]
	v_mul_f32_e32 v68, 0xbfb8aa3b, v58
	v_mul_f32_e32 v69, 0xbfb8aa3b, v59
	v_exp_f32_e32 v68, v68
	v_exp_f32_e32 v69, v69
	v_pk_mul_f32 v[62:63], v[62:63], v[0:1] op_sel_hi:[1,0]
	v_pk_mul_f32 v[54:55], v[54:55], v[0:1] op_sel_hi:[1,0]
	v_add_f32_e32 v68, 1.0, v68
	v_add_f32_e32 v69, 1.0, v69
	v_rcp_f32_e32 v68, v68
	v_rcp_f32_e32 v69, v69
	v_pk_mul_f32 v[64:65], v[64:65], v[0:1] op_sel_hi:[1,0]
	v_pk_mul_f32 v[56:57], v[56:57], v[0:1] op_sel_hi:[1,0]
	v_pk_mul_f32 v[52:53], v[52:53], v[0:1] op_sel_hi:[1,0]
	v_pk_mul_f32 v[58:59], v[58:59], v[68:69]
	v_pk_mul_f32 v[50:51], v[50:51], v[0:1] op_sel_hi:[1,0]
	v_pk_mul_f32 v[62:63], v[62:63], v[58:59]
	v_mul_f32_e32 v58, 0xbfb8aa3b, v60
	v_mul_f32_e32 v59, 0xbfb8aa3b, v61
	v_exp_f32_e32 v58, v58
	v_exp_f32_e32 v59, v59
	v_mul_f32_e32 v0, 0xbfb8aa3b, v54
	v_exp_f32_e32 v0, v0
	v_add_f32_e32 v58, 1.0, v58
	v_add_f32_e32 v59, 1.0, v59
	v_rcp_f32_e32 v58, v58
	v_rcp_f32_e32 v59, v59
	v_add_f32_e32 v0, 1.0, v0
	v_cvt_pk_bf16_f32 v62, v62, v63
	v_mad_i64_i32 v[66:67], s[12:13], v74, s15, v[134:135]
	v_pk_mul_f32 v[58:59], v[60:61], v[58:59]
	s_nop 0
	v_pk_mul_f32 v[60:61], v[64:65], v[58:59]
	v_lshl_add_u64 v[58:59], v[66:67], 0, s[10:11]
	v_cvt_pk_bf16_f32 v63, v60, v61
	v_rcp_f32_e32 v60, v0
	v_mul_f32_e32 v0, 0xbfb8aa3b, v55
	v_exp_f32_e32 v0, v0
	global_store_dwordx2 v[58:59], v[62:63], off
	v_add_f32_e32 v0, 1.0, v0
	v_rcp_f32_e32 v61, v0
	v_mul_f32_e32 v0, 0xbfb8aa3b, v56
	v_exp_f32_e32 v0, v0
	v_pk_mul_f32 v[54:55], v[54:55], v[60:61]
	s_nop 0
	v_pk_mul_f32 v[50:51], v[50:51], v[54:55]
	v_add_f32_e32 v0, 1.0, v0
	v_rcp_f32_e32 v54, v0
	v_mul_f32_e32 v0, 0xbfb8aa3b, v57
	v_exp_f32_e32 v0, v0
	v_cvt_pk_bf16_f32 v50, v50, v51
	v_add_f32_e32 v0, 1.0, v0
	v_rcp_f32_e32 v55, v0
	s_nop 0
	v_pk_mul_f32 v[54:55], v[56:57], v[54:55]
	s_nop 0
	v_pk_mul_f32 v[52:53], v[52:53], v[54:55]
	s_nop 0
	v_cvt_pk_bf16_f32 v51, v52, v53
	global_store_dwordx2 v[58:59], v[50:51], off offset:128
	v_add_u32_e32 v58, 0x90, v136
	v_ashrrev_i32_e32 v59, 31, v58
	v_lshlrev_b64 v[50:51], 5, v[58:59]
	v_lshl_add_u64 v[54:55], s[4:5], 0, v[50:51]
	s_nop 0
	s_waitcnt vmcnt(4)
; DI float sigmoidf_(float x) { return frcp(1.f + __expf(-x)); }
; DI void st_bf16x4(bf16_t* p, f32x4 v) { u32x2 o; o.x = pk2e(v[0], v[1]); o.y = pk2e(v[2], v[3]); *(u32x2*)p = o; }
;   DI float operator()(int row, int colbase, int fq, f32x4 v0, f32x4 v1) const { one(row, colbase + 4 * fq, v0); one(row, colbase + 16 + 4 * fq, v1); return 0.f; }
;   DI float operator()(int row, int colbase, int fq, f32x4 v0, f32x4 v1) const { one(row, colbase + 4 * fq, v0); one(row, colbase + 16 + 4 * fq, v1); return 0.f; }
;   DI float operator()(int row, int colbase, int fq, f32x4 v0, f32x4 v1) const { one(row, colbase + 4 * fq, v0); one(row, colbase + 16 + 4 * fq, v1); return 0.f; }
;   DI float operator()(int row, int colbase, int fq, f32x4 v0, f32x4 v1) const { one(row, colbase + 4 * fq, v0); one(row, colbase + 16 + 4 * fq, v1); return 0.f; }
;     ...
;       for (int m = 0; m < 4; ++m) {
;         const int row = brow + ai * HALF + wr * 64 + m * 16 + fr_e;
;         const float rsc = epi.rowscale(row);
;         float ssq = 0.f;
; #pragma unroll
;         for (int bj = 0; bj < 2; ++bj)
;           ssq += epi(row, bcol + bj * HALF + wc * 32, fq_e, acc[ai][bj][m][0] * rsc, acc[ai][bj][m][1] * rsc);
;   DI float rowscale(int row) const { const f32x4 a = *(const f32x4*)(ssp_in + (size_t)row * 8), b = *(const f32x4*)(ssp_in + (size_t)row * 8 + 4);
;     return rsqrtf((((a[0] + a[1]) + (a[2] + a[3])) + ((b[0] + b[1]) + (b[2] + b[3]))) * (1.f / D_) + EPS_); }
;   DI float operator()(int row, int colbase, int fq, f32x4 v0, f32x4 v1) const {
;     f32x4 r;
; #pragma unroll
;     for (int e = 0; e < 4; ++e) r[e] = v0[e] * sigmoidf_(v0[e]) * v1[e];
;     st_bf16x4(hid + (size_t)row * FFN_ + (colbase >> 1) + 4 * fq, r); return 0.f;
	v_mov_b32_e32 v60, v216
	v_mov_b32_e32 v61, v220
	v_mov_b32_e32 v220, v217
	v_pk_add_f32 v[216:217], v[60:61], v[220:221]
	v_mov_b32_e32 v220, v218
	v_mov_b32_e32 v221, v222
	v_mov_b32_e32 v222, v219
	v_pk_add_f32 v[218:219], v[220:221], v[222:223]
	s_nop 0
	v_pk_add_f32 v[216:217], v[216:217], v[218:219]
	s_nop 0
	v_add_f32_e32 v0, v216, v217
	v_fmamk_f32 v0, v0, 0x3a000000, v249
	v_cmp_gt_f32_e32 vcc, s14, v0
	v_mul_f32_e32 v50, 0x4b800000, v0
	s_nop 0
	v_cndmask_b32_e32 v0, v0, v50, vcc
	v_rsq_f32_e32 v0, v0
	s_nop 0
	v_mul_f32_e32 v50, 0x45800000, v0
	v_cndmask_b32_e32 v0, v0, v50, vcc
	v_pk_mul_f32 v[42:43], v[42:43], v[0:1] op_sel_hi:[1,0]
	v_pk_mul_f32 v[44:45], v[44:45], v[0:1] op_sel_hi:[1,0]
	v_mul_f32_e32 v52, 0xbfb8aa3b, v42
	v_mul_f32_e32 v53, 0xbfb8aa3b, v43
	v_exp_f32_e32 v52, v52
	v_exp_f32_e32 v53, v53
	v_pk_mul_f32 v[46:47], v[46:47], v[0:1] op_sel_hi:[1,0]
	v_pk_mul_f32 v[38:39], v[38:39], v[0:1] op_sel_hi:[1,0]
	v_add_f32_e32 v52, 1.0, v52
	v_add_f32_e32 v53, 1.0, v53
	v_rcp_f32_e32 v52, v52
	v_rcp_f32_e32 v53, v53
	v_pk_mul_f32 v[48:49], v[48:49], v[0:1] op_sel_hi:[1,0]
	v_pk_mul_f32 v[40:41], v[40:41], v[0:1] op_sel_hi:[1,0]
	v_pk_mul_f32 v[36:37], v[36:37], v[0:1] op_sel_hi:[1,0]
	v_pk_mul_f32 v[42:43], v[42:43], v[52:53]
	v_pk_mul_f32 v[34:35], v[34:35], v[0:1] op_sel_hi:[1,0]
	v_pk_mul_f32 v[46:47], v[46:47], v[42:43]
	v_mul_f32_e32 v42, 0xbfb8aa3b, v44
	v_mul_f32_e32 v43, 0xbfb8aa3b, v45
	v_exp_f32_e32 v42, v42
	v_exp_f32_e32 v43, v43
	v_mul_f32_e32 v0, 0xbfb8aa3b, v38
	v_exp_f32_e32 v0, v0
	v_add_f32_e32 v42, 1.0, v42
	v_add_f32_e32 v43, 1.0, v43
	v_rcp_f32_e32 v42, v42
	v_rcp_f32_e32 v43, v43
	v_add_f32_e32 v0, 1.0, v0
	v_cvt_pk_bf16_f32 v46, v46, v47
	v_mad_i64_i32 v[50:51], s[12:13], v58, s15, v[134:135]
	v_pk_mul_f32 v[42:43], v[44:45], v[42:43]
	s_nop 0
	v_pk_mul_f32 v[44:45], v[48:49], v[42:43]
	v_lshl_add_u64 v[42:43], v[50:51], 0, s[10:11]
	v_cvt_pk_bf16_f32 v47, v44, v45
	v_rcp_f32_e32 v44, v0
	v_mul_f32_e32 v0, 0xbfb8aa3b, v39
	v_exp_f32_e32 v0, v0
	global_store_dwordx2 v[42:43], v[46:47], off
	v_add_f32_e32 v0, 1.0, v0
	v_rcp_f32_e32 v45, v0
	v_mul_f32_e32 v0, 0xbfb8aa3b, v40
	v_exp_f32_e32 v0, v0
	v_pk_mul_f32 v[38:39], v[38:39], v[44:45]
	s_nop 0
	v_pk_mul_f32 v[34:35], v[34:35], v[38:39]
	v_add_f32_e32 v0, 1.0, v0
	v_rcp_f32_e32 v38, v0
	v_mul_f32_e32 v0, 0xbfb8aa3b, v41
	v_exp_f32_e32 v0, v0
	v_cvt_pk_bf16_f32 v34, v34, v35
	v_add_f32_e32 v0, 1.0, v0
	v_rcp_f32_e32 v39, v0
	s_nop 0
	v_pk_mul_f32 v[38:39], v[40:41], v[38:39]
	s_nop 0
	v_pk_mul_f32 v[36:37], v[36:37], v[38:39]
	s_nop 0
	v_cvt_pk_bf16_f32 v35, v36, v37
	global_store_dwordx2 v[42:43], v[34:35], off offset:128
	v_add_u32_e32 v42, 0xa0, v136
	v_ashrrev_i32_e32 v43, 31, v42
	v_lshlrev_b64 v[34:35], 5, v[42:43]
	v_lshl_add_u64 v[38:39], s[4:5], 0, v[34:35]
	s_nop 0
	s_waitcnt vmcnt(2)
; #define TIDX launder((int)threadIdx.x)
; DI float shx(float v, int mask) { return __int_as_float(__builtin_amdgcn_ds_bpermute((lane_now() ^ mask) << 2, __float_as_int(v))); }
; DI float sigmoidf_(float x) { return frcp(1.f + __expf(-x)); }
; #define LAS __attribute__((address_space(3)))
; DI void st_bf16x4(bf16_t* p, f32x4 v) { u32x2 o; o.x = pk2e(v[0], v[1]); o.y = pk2e(v[2], v[3]); *(u32x2*)p = o; }
;   DI float operator()(int row, int colbase, int fq, f32x4 v0, f32x4 v1) const { one(row, colbase + 4 * fq, v0); one(row, colbase + 16 + 4 * fq, v1); return 0.f; }
;   DI float operator()(int row, int colbase, int fq, f32x4 v0, f32x4 v1) const { one(row, colbase + 4 * fq, v0); one(row, colbase + 16 + 4 * fq, v1); return 0.f; }
;     ...
;       for (int m = 0; m < 4; ++m) {
;         const int row = brow + ai * HALF + wr * 64 + m * 16 + fr_e;
;         const float rsc = epi.rowscale(row);
;         float ssq = 0.f;
; #pragma unroll
;         for (int bj = 0; bj < 2; ++bj)
;           ssq += epi(row, bcol + bj * HALF + wc * 32, fq_e, acc[ai][bj][m][0] * rsc, acc[ai][bj][m][1] * rsc);
;         rowss[ai][m] = ssq;
;         __builtin_amdgcn_sched_barrier(0);
;       }
;     if constexpr (Epi::HAS_SS) {
;       float* ssp = epi.ssp_ptr();
;       if (ssp) {
;         LAS float* red = (LAS float*)lds;
; #pragma unroll
;         for (int ai = 0; ai < 2; ++ai)
; #pragma unroll
;           for (int m = 0; m < 4; ++m) {
;             float v = rowss[ai][m];
;             v += shx(v, 16); v += shx(v, 32);
;             if (fq_e == 0) red[(ai * HALF + wr * 64 + m * 16 + fr_e) * 4 + wc] = v;
;           }
;         __syncthreads();
;         { const int t2 = TIDX; if (t2 < 256) { const LAS float* q = red + t2 * 4; ssp[(size_t)(brow + t2) * 8 + pn] = (q[0] + q[1]) + (q[2] + q[3]); } }
;       }
;     }
;     __syncthreads();
;   }
;   DI float rowscale(int row) const { const f32x4 a = *(const f32x4*)(ssp_in + (size_t)row * 8), b = *(const f32x4*)(ssp_in + (size_t)row * 8 + 4);
;     return rsqrtf((((a[0] + a[1]) + (a[2] + a[3])) + ((b[0] + b[1]) + (b[2] + b[3]))) * (1.f / D_) + EPS_); }
;   DI float operator()(int row, int colbase, int fq, f32x4 v0, f32x4 v1) const {
;     f32x4 r;
; #pragma unroll
;     for (int e = 0; e < 4; ++e) r[e] = v0[e] * sigmoidf_(v0[e]) * v1[e];
;     st_bf16x4(hid + (size_t)row * FFN_ + (colbase >> 1) + 4 * fq, r); return 0.f;
	v_mov_b32_e32 v44, v224
	v_mov_b32_e32 v45, v228
	v_mov_b32_e32 v228, v225
	v_pk_add_f32 v[224:225], v[44:45], v[228:229]
	v_mov_b32_e32 v228, v226
	v_mov_b32_e32 v229, v230
	v_mov_b32_e32 v230, v227
	v_pk_add_f32 v[226:227], v[228:229], v[230:231]
	s_nop 0
	v_pk_add_f32 v[224:225], v[224:225], v[226:227]
	s_nop 0
	v_add_f32_e32 v0, v224, v225
	v_fmamk_f32 v0, v0, 0x3a000000, v249
	v_cmp_gt_f32_e32 vcc, s14, v0
	v_mul_f32_e32 v34, 0x4b800000, v0
	s_nop 0
	v_cndmask_b32_e32 v0, v0, v34, vcc
	v_rsq_f32_e32 v0, v0
	s_nop 0
	v_mul_f32_e32 v34, 0x45800000, v0
	v_cndmask_b32_e32 v0, v0, v34, vcc
	v_pk_mul_f32 v[26:27], v[26:27], v[0:1] op_sel_hi:[1,0]
	v_pk_mul_f32 v[28:29], v[28:29], v[0:1] op_sel_hi:[1,0]
	v_mul_f32_e32 v36, 0xbfb8aa3b, v26
	v_mul_f32_e32 v37, 0xbfb8aa3b, v27
	v_exp_f32_e32 v36, v36
	v_exp_f32_e32 v37, v37
	v_pk_mul_f32 v[30:31], v[30:31], v[0:1] op_sel_hi:[1,0]
	v_pk_mul_f32 v[22:23], v[22:23], v[0:1] op_sel_hi:[1,0]
	v_add_f32_e32 v36, 1.0, v36
	v_add_f32_e32 v37, 1.0, v37
	v_rcp_f32_e32 v36, v36
	v_rcp_f32_e32 v37, v37
	v_pk_mul_f32 v[32:33], v[32:33], v[0:1] op_sel_hi:[1,0]
	v_pk_mul_f32 v[24:25], v[24:25], v[0:1] op_sel_hi:[1,0]
	v_pk_mul_f32 v[20:21], v[20:21], v[0:1] op_sel_hi:[1,0]
	v_pk_mul_f32 v[26:27], v[26:27], v[36:37]
	v_pk_mul_f32 v[18:19], v[18:19], v[0:1] op_sel_hi:[1,0]
	v_pk_mul_f32 v[30:31], v[30:31], v[26:27]
	v_mul_f32_e32 v26, 0xbfb8aa3b, v28
	v_mul_f32_e32 v27, 0xbfb8aa3b, v29
	v_exp_f32_e32 v26, v26
	v_exp_f32_e32 v27, v27
	v_mul_f32_e32 v0, 0xbfb8aa3b, v22
	v_exp_f32_e32 v0, v0
	v_add_f32_e32 v26, 1.0, v26
	v_add_f32_e32 v27, 1.0, v27
	v_rcp_f32_e32 v26, v26
	v_rcp_f32_e32 v27, v27
	v_add_f32_e32 v0, 1.0, v0
	v_cvt_pk_bf16_f32 v30, v30, v31
	v_mad_i64_i32 v[34:35], s[12:13], v42, s15, v[134:135]
	v_pk_mul_f32 v[26:27], v[28:29], v[26:27]
	s_nop 0
	v_pk_mul_f32 v[28:29], v[32:33], v[26:27]
	v_lshl_add_u64 v[26:27], v[34:35], 0, s[10:11]
	v_cvt_pk_bf16_f32 v31, v28, v29
	v_rcp_f32_e32 v28, v0
	v_mul_f32_e32 v0, 0xbfb8aa3b, v23
	v_exp_f32_e32 v0, v0
	global_store_dwordx2 v[26:27], v[30:31], off
	v_add_f32_e32 v0, 1.0, v0
	v_rcp_f32_e32 v29, v0
	v_mul_f32_e32 v0, 0xbfb8aa3b, v24
	v_exp_f32_e32 v0, v0
	v_pk_mul_f32 v[22:23], v[22:23], v[28:29]
	s_nop 0
	v_pk_mul_f32 v[18:19], v[18:19], v[22:23]
	v_add_f32_e32 v0, 1.0, v0
	v_rcp_f32_e32 v22, v0
	v_mul_f32_e32 v0, 0xbfb8aa3b, v25
	v_exp_f32_e32 v0, v0
	v_cvt_pk_bf16_f32 v18, v18, v19
	v_add_f32_e32 v0, 1.0, v0
	v_rcp_f32_e32 v23, v0
	s_nop 0
	v_pk_mul_f32 v[22:23], v[24:25], v[22:23]
	s_nop 0
	v_pk_mul_f32 v[20:21], v[20:21], v[22:23]
	s_nop 0
	v_cvt_pk_bf16_f32 v19, v20, v21
	global_store_dwordx2 v[26:27], v[18:19], off offset:128
	v_add_u32_e32 v26, 0xb0, v136
	v_ashrrev_i32_e32 v27, 31, v26
	v_lshlrev_b64 v[18:19], 5, v[26:27]
	v_lshl_add_u64 v[22:23], s[4:5], 0, v[18:19]
	s_nop 0
	s_mov_b32 s84, 0x800000
	s_waitcnt vmcnt(0)
	v_mov_b32_e32 v28, v232
	v_mov_b32_e32 v29, v236
	v_mov_b32_e32 v236, v233
	v_pk_add_f32 v[232:233], v[28:29], v[236:237]
	v_mov_b32_e32 v236, v234
	v_mov_b32_e32 v237, v238
	v_mov_b32_e32 v238, v235
	v_pk_add_f32 v[234:235], v[236:237], v[238:239]
	s_nop 0
	v_pk_add_f32 v[232:233], v[232:233], v[234:235]
	s_nop 0
	v_add_f32_e32 v0, v232, v233
	v_fmamk_f32 v0, v0, 0x3a000000, v249
	v_cmp_gt_f32_e32 vcc, s14, v0
	v_mul_f32_e32 v18, 0x4b800000, v0
	s_nop 0
	v_cndmask_b32_e32 v0, v0, v18, vcc
	v_rsq_f32_e32 v0, v0
	s_nop 0
	v_mul_f32_e32 v18, 0x45800000, v0
	v_cndmask_b32_e32 v0, v0, v18, vcc
	v_pk_mul_f32 v[10:11], v[10:11], v[0:1] op_sel_hi:[1,0]
	v_pk_mul_f32 v[12:13], v[12:13], v[0:1] op_sel_hi:[1,0]
	v_mul_f32_e32 v20, 0xbfb8aa3b, v10
	v_mul_f32_e32 v21, 0xbfb8aa3b, v11
	v_exp_f32_e32 v20, v20
	v_exp_f32_e32 v21, v21
	v_pk_mul_f32 v[14:15], v[14:15], v[0:1] op_sel_hi:[1,0]
	v_pk_mul_f32 v[6:7], v[6:7], v[0:1] op_sel_hi:[1,0]
	v_add_f32_e32 v20, 1.0, v20
	v_add_f32_e32 v21, 1.0, v21
	v_rcp_f32_e32 v20, v20
	v_rcp_f32_e32 v21, v21
	v_pk_mul_f32 v[16:17], v[16:17], v[0:1] op_sel_hi:[1,0]
	v_pk_mul_f32 v[8:9], v[8:9], v[0:1] op_sel_hi:[1,0]
	v_pk_mul_f32 v[4:5], v[4:5], v[0:1] op_sel_hi:[1,0]
	v_pk_mul_f32 v[10:11], v[10:11], v[20:21]
	v_pk_mul_f32 v[2:3], v[2:3], v[0:1] op_sel_hi:[1,0]
	v_pk_mul_f32 v[14:15], v[14:15], v[10:11]
	v_mul_f32_e32 v10, 0xbfb8aa3b, v12
	v_mul_f32_e32 v11, 0xbfb8aa3b, v13
	v_exp_f32_e32 v10, v10
	v_exp_f32_e32 v11, v11
	v_mul_f32_e32 v0, 0xbfb8aa3b, v6
	v_exp_f32_e32 v0, v0
	v_add_f32_e32 v10, 1.0, v10
	v_add_f32_e32 v11, 1.0, v11
	v_rcp_f32_e32 v10, v10
	v_rcp_f32_e32 v11, v11
	v_add_f32_e32 v0, 1.0, v0
	v_cvt_pk_bf16_f32 v14, v14, v15
	v_mad_i64_i32 v[18:19], s[12:13], v26, s15, v[134:135]
	v_pk_mul_f32 v[10:11], v[12:13], v[10:11]
	s_nop 0
	v_pk_mul_f32 v[12:13], v[16:17], v[10:11]
	v_lshl_add_u64 v[10:11], v[18:19], 0, s[10:11]
	v_cvt_pk_bf16_f32 v15, v12, v13
	v_rcp_f32_e32 v12, v0
	v_mul_f32_e32 v0, 0xbfb8aa3b, v7
	v_exp_f32_e32 v0, v0
	global_store_dwordx2 v[10:11], v[14:15], off
	v_add_f32_e32 v0, 1.0, v0
	v_rcp_f32_e32 v13, v0
	v_mul_f32_e32 v0, 0xbfb8aa3b, v8
	v_exp_f32_e32 v0, v0
	v_pk_mul_f32 v[6:7], v[6:7], v[12:13]
	s_nop 0
	v_pk_mul_f32 v[2:3], v[2:3], v[6:7]
	v_add_f32_e32 v0, 1.0, v0
	v_rcp_f32_e32 v6, v0
	v_mul_f32_e32 v0, 0xbfb8aa3b, v9
	v_exp_f32_e32 v0, v0
	v_cvt_pk_bf16_f32 v2, v2, v3
	v_add_f32_e32 v0, 1.0, v0
	v_rcp_f32_e32 v7, v0
	s_nop 0
	v_pk_mul_f32 v[6:7], v[8:9], v[6:7]
	s_nop 0
	v_pk_mul_f32 v[4:5], v[4:5], v[6:7]
	s_nop 0
	v_cvt_pk_bf16_f32 v3, v4, v5
	global_store_dwordx2 v[10:11], v[2:3], off offset:128
	v_readlane_b32 s10, v250, 1
	s_add_i32 s31, s31, s10
	s_cmpk_gt_i32 s31, 0x57f
	s_barrier
	v_readlane_b32 s11, v250, 2
	s_cbranch_scc1 .LBB0_31

; DI void st_bf16x4(bf16_t* p, f32x4 v) { u32x2 o; o.x = pk2e(v[0], v[1]); o.y = pk2e(v[2], v[3]); *(u32x2*)p = o; }
; DI void st_tr4(bf16_t* p, size_t stride, f32x4 v) { p[0] = f2bf(v[0]); p[stride] = f2bf(v[1]); p[2 * stride] = f2bf(v[2]); p[3 * stride] = f2bf(v[3]); }
;     ...
;       for (int m = 0; m < 4; ++m) {
;         const int row = brow + ai * HALF + wr * 64 + m * 16 + fr_e;
;         const float rsc = epi.rowscale(row);
;         float ssq = 0.f;
; #pragma unroll
;         for (int bj = 0; bj < 2; ++bj)
;           ssq += epi(row, bcol + bj * HALF + wc * 32, fq_e, acc[ai][bj][m][0] * rsc, acc[ai][bj][m][1] * rsc);
;   DI float rowscale(int row) const { const f32x4 a = *(const f32x4*)(ssp_in + (size_t)row * 8), b = *(const f32x4*)(ssp_in + (size_t)row * 8 + 4);
;     return rsqrtf((((a[0] + a[1]) + (a[2] + a[3])) + ((b[0] + b[1]) + (b[2] + b[3]))) * (1.f / D_) + EPS_); }
;   DI void one(int row, int c, f32x4 v) const {
;     const int b = row >> 12, t = row & 4095;
;     if (c < 2048) { const int h = c >> 7, d = c & 127; st_bf16x4((bf16_t*)(ws + O_NQ) + ((size_t)(b * 16 + h) * T_ + t) * 128 + d, v); }
;     else if (c < 5120) {
;       const int seg = (c - 2048) >> 9, cc = (c - 2048) & 511, g = cc >> 7, d = cc & 127;
;       if (seg == 3 || seg == 5) st_tr4((bf16_t*)(ws + (seg == 3 ? O_VST : O_VWT)) + (size_t)(b * 4 + g) * 128 * T_ + (size_t)(t >> 5) * 4096 + d * 32 + ((((t & 31) >> 2) ^ ((d >> 2) & 7)) << 2) + (t & 3), 32, v);
;       else { const size_t off = seg == 0 ? O_KC : seg == 1 ? O_VC : seg == 2 ? O_KS : O_KW;
;         st_bf16x4((bf16_t*)(ws + off) + ((size_t)(b * 4 + g) * T_ + t) * 128 + d, v); }
;     } else if (c < 5168) { *(f32x4*)((float*)(ws + O_GT) + (size_t)row * 48 + (c - 5120)) = v; }
.LBB0_452:
	v_mov_b32_e32 v148, v199
	s_add_i32 s9, s0, s20
	v_and_b32_e32 v149, 15, v148
	v_or_b32_e32 v142, s9, v149
	v_ashrrev_i32_e32 v143, 31, v142
	v_readlane_b32 s0, v253, 52
	v_lshlrev_b64 v[134:135], 5, v[142:143]
	v_readlane_b32 s1, v253, 53
	v_lshrrev_b32_e32 v152, 2, v148
	v_and_b32_e32 v155, 12, v152
	v_lshl_add_u64 v[138:139], s[0:1], 0, v[134:135]
	s_mov_b64 s[100:101], 0x1000
	v_lshl_add_u64 v[240:241], v[138:139], 0, s[100:101]
	global_load_dwordx4 v[162:165], v[240:241], off offset:-4096
	global_load_dwordx4 v[166:169], v[240:241], off offset:-4080
	global_load_dwordx4 v[170:173], v[240:241], off offset:-3584
	global_load_dwordx4 v[174:177], v[240:241], off offset:-3568
	global_load_dwordx4 v[178:181], v[240:241], off offset:-3072
	global_load_dwordx4 v[182:185], v[240:241], off offset:-3056
	global_load_dwordx4 v[200:203], v[240:241], off offset:-2560
	global_load_dwordx4 v[204:207], v[240:241], off offset:-2544
	global_load_dwordx4 v[208:211], v[240:241], off
	global_load_dwordx4 v[212:215], v[240:241], off offset:16
	global_load_dwordx4 v[216:219], v[240:241], off offset:512
	global_load_dwordx4 v[220:223], v[240:241], off offset:528
	global_load_dwordx4 v[224:227], v[240:241], off offset:1024
	global_load_dwordx4 v[228:231], v[240:241], off offset:1040
	global_load_dwordx4 v[232:235], v[240:241], off offset:1536
	global_load_dwordx4 v[236:239], v[240:241], off offset:1552
	s_nop 0
	v_readlane_b32 s0, v253, 48
	v_readlane_b32 s1, v253, 49
	v_or_b32_e32 v147, s8, v155
	s_ashr_i32 s30, s9, 12
	v_and_b32_e32 v146, 3, v148
	s_lshl_b32 s29, s30, 2
	v_bitop3_b32 v148, v152, 12, v148 bitop3:0x48
	s_waitcnt vmcnt(14)
	v_mov_b32_e32 v150, v162
	v_mov_b32_e32 v151, v166
	v_mov_b32_e32 v166, v163
	v_pk_add_f32 v[162:163], v[150:151], v[166:167]
	v_mov_b32_e32 v166, v164
	v_mov_b32_e32 v167, v168
	v_mov_b32_e32 v168, v165
	v_pk_add_f32 v[164:165], v[166:167], v[168:169]
	s_nop 0
	v_pk_add_f32 v[162:163], v[162:163], v[164:165]
	s_nop 0
	v_add_f32_e32 v0, v162, v163
	v_fmamk_f32 v0, v0, 0x3a000000, v249
	v_cmp_gt_f32_e32 vcc, s84, v0
	v_mul_f32_e32 v134, 0x4b800000, v0
	s_nop 0
	v_cndmask_b32_e32 v0, v0, v134, vcc
	v_rsq_f32_e32 v0, v0
	s_nop 0
	v_mul_f32_e32 v134, 0x45800000, v0
	v_cndmask_b32_e32 v138, v0, v134, vcc
	v_mov_b64_e32 v[134:135], s[0:1]
	v_mad_i64_i32 v[140:141], s[0:1], v142, s75, v[134:135]
	v_lshlrev_b32_e32 v134, 7, v142
	v_and_b32_e32 v0, 0x7e780, v134
	v_and_b32_e32 v156, 0x7e000, v134
	v_or_b32_e32 v134, s21, v147
	s_movk_i32 s0, 0x7ff
	v_pk_mul_f32 v[128:129], v[128:129], v[138:139] op_sel_hi:[1,0]
	v_pk_mul_f32 v[126:127], v[126:127], v[138:139] op_sel_hi:[1,0]
	v_cmp_lt_i32_e64 s[38:39], s0, v134
	s_and_saveexec_b64 s[0:1], s[38:39]
	s_xor_b64 s[10:11], exec, s[0:1]
	s_cbranch_execz .LBB0_467
	s_cmpk_gt_u32 s8, 0x13ff
	s_mov_b64 s[0:1], -1
	s_cbranch_scc0 .LBB0_457
	s_movk_i32 s0, 0x1430
	v_cmp_gt_u32_e32 vcc, s0, v134
	s_and_saveexec_b64 s[0:1], vcc
	s_cbranch_execz .LBB0_456
	v_mov_b32_e32 v135, v1
	v_lshl_add_u64 v[136:137], v[134:135], 2, v[140:141]
	v_add_co_u32_e32 v136, vcc, 0x2a160000, v136
	s_nop 1
	v_addc_co_u32_e32 v137, vcc, 0, v137, vcc
	global_store_dwordx4 v[136:137], v[126:129], off

; DI void st_bf16x4(bf16_t* p, f32x4 v) { u32x2 o; o.x = pk2e(v[0], v[1]); o.y = pk2e(v[2], v[3]); *(u32x2*)p = o; }
; DI void st_tr4(bf16_t* p, size_t stride, f32x4 v) { p[0] = f2bf(v[0]); p[stride] = f2bf(v[1]); p[2 * stride] = f2bf(v[2]); p[3 * stride] = f2bf(v[3]); }
;     ...
;       for (int m = 0; m < 4; ++m) {
;         const int row = brow + ai * HALF + wr * 64 + m * 16 + fr_e;
;         const float rsc = epi.rowscale(row);
;         float ssq = 0.f;
; #pragma unroll
;         for (int bj = 0; bj < 2; ++bj)
;           ssq += epi(row, bcol + bj * HALF + wc * 32, fq_e, acc[ai][bj][m][0] * rsc, acc[ai][bj][m][1] * rsc);
;   DI float rowscale(int row) const { const f32x4 a = *(const f32x4*)(ssp_in + (size_t)row * 8), b = *(const f32x4*)(ssp_in + (size_t)row * 8 + 4);
;     return rsqrtf((((a[0] + a[1]) + (a[2] + a[3])) + ((b[0] + b[1]) + (b[2] + b[3]))) * (1.f / D_) + EPS_); }
;   DI void one(int row, int c, f32x4 v) const {
;     const int b = row >> 12, t = row & 4095;
;     if (c < 2048) { const int h = c >> 7, d = c & 127; st_bf16x4((bf16_t*)(ws + O_NQ) + ((size_t)(b * 16 + h) * T_ + t) * 128 + d, v); }
;     else if (c < 5120) {
;       const int seg = (c - 2048) >> 9, cc = (c - 2048) & 511, g = cc >> 7, d = cc & 127;
;       if (seg == 3 || seg == 5) st_tr4((bf16_t*)(ws + (seg == 3 ? O_VST : O_VWT)) + (size_t)(b * 4 + g) * 128 * T_ + (size_t)(t >> 5) * 4096 + d * 32 + ((((t & 31) >> 2) ^ ((d >> 2) & 7)) << 2) + (t & 3), 32, v);
;       else { const size_t off = seg == 0 ? O_KC : seg == 1 ? O_VC : seg == 2 ? O_KS : O_KW;
;         st_bf16x4((bf16_t*)(ws + off) + ((size_t)(b * 4 + g) * T_ + t) * 128 + d, v); }
;     } else if (c < 5168) { *(f32x4*)((float*)(ws + O_GT) + (size_t)row * 48 + (c - 5120)) = v; }
.LBB0_520:
	s_or_b64 exec, exec, s[0:1]
	v_or_b32_e32 v141, 16, v149
	v_or_b32_e32 v120, s9, v141
	v_ashrrev_i32_e32 v121, 31, v120
	v_readlane_b32 s0, v253, 52
	v_lshlrev_b64 v[114:115], 5, v[120:121]
	v_readlane_b32 s1, v253, 53
	v_bitop3_b32 v140, v141, v155, 28 bitop3:0x6c
	s_nop 0
	v_lshl_add_u64 v[142:143], s[0:1], 0, v[114:115]
	v_readlane_b32 s0, v253, 48
	v_readlane_b32 s1, v253, 49
	s_waitcnt vmcnt(12)
	v_mov_b32_e32 v142, v170
	v_mov_b32_e32 v143, v174
	v_mov_b32_e32 v174, v171
	v_pk_add_f32 v[170:171], v[142:143], v[174:175]
	v_mov_b32_e32 v142, v172
	v_mov_b32_e32 v143, v176
	v_mov_b32_e32 v176, v173
	v_pk_add_f32 v[172:173], v[142:143], v[176:177]
	s_nop 0
	v_pk_add_f32 v[170:171], v[170:171], v[172:173]
	v_mov_b64_e32 v[116:117], s[0:1]
	v_add_f32_e32 v0, v170, v171
	v_fmamk_f32 v0, v0, 0x3a000000, v249
	v_cmp_gt_f32_e32 vcc, s84, v0
	v_mul_f32_e32 v114, 0x4b800000, v0
	v_lshlrev_b32_e32 v115, 7, v120
	v_cndmask_b32_e32 v0, v0, v114, vcc
	v_rsq_f32_e32 v0, v0
	v_mad_i64_i32 v[116:117], s[0:1], v120, s75, v[116:117]
	v_and_b32_e32 v142, 0x7e000, v115
	v_mul_f32_e32 v114, 0x45800000, v0
	v_cndmask_b32_e32 v114, v0, v114, vcc
	v_and_b32_e32 v0, 0x7ef80, v115
	v_pk_mul_f32 v[112:113], v[112:113], v[114:115] op_sel_hi:[1,0]
	v_pk_mul_f32 v[110:111], v[110:111], v[114:115] op_sel_hi:[1,0]
	s_and_saveexec_b64 s[0:1], s[38:39]
	s_xor_b64 s[10:11], exec, s[0:1]
	s_cbranch_execz .LBB0_535
	s_cmpk_lt_u32 s8, 0x1400
	s_mov_b64 s[0:1], -1
	s_cbranch_scc1 .LBB0_525
	s_movk_i32 s0, 0x1430
	v_cmp_gt_u32_e32 vcc, s0, v134
	s_and_saveexec_b64 s[0:1], vcc
	s_cbranch_execz .LBB0_524
	v_mov_b32_e32 v135, v1
	v_lshl_add_u64 v[120:121], v[134:135], 2, v[116:117]
	v_add_co_u32_e32 v120, vcc, 0x2a160000, v120
	s_nop 1
	v_addc_co_u32_e32 v121, vcc, 0, v121, vcc
	global_store_dwordx4 v[120:121], v[110:113], off

; DI void st_bf16x4(bf16_t* p, f32x4 v) { u32x2 o; o.x = pk2e(v[0], v[1]); o.y = pk2e(v[2], v[3]); *(u32x2*)p = o; }
; DI void st_tr4(bf16_t* p, size_t stride, f32x4 v) { p[0] = f2bf(v[0]); p[stride] = f2bf(v[1]); p[2 * stride] = f2bf(v[2]); p[3 * stride] = f2bf(v[3]); }
;     ...
;       for (int m = 0; m < 4; ++m) {
;         const int row = brow + ai * HALF + wr * 64 + m * 16 + fr_e;
;         const float rsc = epi.rowscale(row);
;         float ssq = 0.f;
; #pragma unroll
;         for (int bj = 0; bj < 2; ++bj)
;           ssq += epi(row, bcol + bj * HALF + wc * 32, fq_e, acc[ai][bj][m][0] * rsc, acc[ai][bj][m][1] * rsc);
;   DI float rowscale(int row) const { const f32x4 a = *(const f32x4*)(ssp_in + (size_t)row * 8), b = *(const f32x4*)(ssp_in + (size_t)row * 8 + 4);
;     return rsqrtf((((a[0] + a[1]) + (a[2] + a[3])) + ((b[0] + b[1]) + (b[2] + b[3]))) * (1.f / D_) + EPS_); }
;   DI void one(int row, int c, f32x4 v) const {
;     const int b = row >> 12, t = row & 4095;
;     if (c < 2048) { const int h = c >> 7, d = c & 127; st_bf16x4((bf16_t*)(ws + O_NQ) + ((size_t)(b * 16 + h) * T_ + t) * 128 + d, v); }
;     else if (c < 5120) {
;       const int seg = (c - 2048) >> 9, cc = (c - 2048) & 511, g = cc >> 7, d = cc & 127;
;       if (seg == 3 || seg == 5) st_tr4((bf16_t*)(ws + (seg == 3 ? O_VST : O_VWT)) + (size_t)(b * 4 + g) * 128 * T_ + (size_t)(t >> 5) * 4096 + d * 32 + ((((t & 31) >> 2) ^ ((d >> 2) & 7)) << 2) + (t & 3), 32, v);
;       else { const size_t off = seg == 0 ? O_KC : seg == 1 ? O_VC : seg == 2 ? O_KS : O_KW;
;         st_bf16x4((bf16_t*)(ws + off) + ((size_t)(b * 4 + g) * T_ + t) * 128 + d, v); }
;     } else if (c < 5168) { *(f32x4*)((float*)(ws + O_GT) + (size_t)row * 48 + (c - 5120)) = v; }
.LBB0_588:
	s_or_b64 exec, exec, s[0:1]
	v_or_b32_e32 v104, 32, v149
	v_or_b32_e32 v102, s9, v104
	v_ashrrev_i32_e32 v103, 31, v102
	v_readlane_b32 s0, v253, 52
	v_lshlrev_b64 v[98:99], 5, v[102:103]
	v_readlane_b32 s1, v253, 53
	s_nop 1
	v_lshl_add_u64 v[106:107], s[0:1], 0, v[98:99]
	s_nop 0
	v_readlane_b32 s0, v253, 48
	v_readlane_b32 s1, v253, 49
	s_waitcnt vmcnt(10)
	v_mov_b32_e32 v110, v178
	v_mov_b32_e32 v111, v182
	v_mov_b32_e32 v182, v179
	v_pk_add_f32 v[178:179], v[110:111], v[182:183]
	v_mov_b32_e32 v182, v180
	v_mov_b32_e32 v183, v184
	v_mov_b32_e32 v184, v181
	v_pk_add_f32 v[180:181], v[182:183], v[184:185]
	s_nop 0
	v_pk_add_f32 v[178:179], v[178:179], v[180:181]
	v_mov_b64_e32 v[100:101], s[0:1]
	v_add_f32_e32 v0, v178, v179
	v_fmamk_f32 v0, v0, 0x3a000000, v249
	v_cmp_gt_f32_e32 vcc, s84, v0
	v_mul_f32_e32 v98, 0x4b800000, v0
	v_lshlrev_b32_e32 v99, 7, v102
	v_cndmask_b32_e32 v0, v0, v98, vcc
	v_rsq_f32_e32 v0, v0
	v_mad_i64_i32 v[100:101], s[0:1], v102, s75, v[100:101]
	v_and_b32_e32 v105, 0x7f000, v99
	v_mul_f32_e32 v98, 0x45800000, v0
	v_cndmask_b32_e32 v98, v0, v98, vcc
	v_and_b32_e32 v0, 0x7f780, v99
	v_pk_mul_f32 v[96:97], v[96:97], v[98:99] op_sel_hi:[1,0]
	v_pk_mul_f32 v[94:95], v[94:95], v[98:99] op_sel_hi:[1,0]
	s_and_saveexec_b64 s[0:1], s[38:39]
	s_xor_b64 s[10:11], exec, s[0:1]
	s_cbranch_execz .LBB0_603
	s_cmpk_lt_u32 s8, 0x1400
	s_mov_b64 s[0:1], -1
	s_cbranch_scc1 .LBB0_593
	s_movk_i32 s0, 0x1430
	v_cmp_gt_u32_e32 vcc, s0, v134
	s_and_saveexec_b64 s[0:1], vcc
	s_cbranch_execz .LBB0_592
	v_mov_b32_e32 v135, v1
	v_lshl_add_u64 v[102:103], v[134:135], 2, v[100:101]
	v_add_co_u32_e32 v102, vcc, 0x2a160000, v102
	s_nop 1
	v_addc_co_u32_e32 v103, vcc, 0, v103, vcc
	global_store_dwordx4 v[102:103], v[94:97], off

; DI void st_bf16x4(bf16_t* p, f32x4 v) { u32x2 o; o.x = pk2e(v[0], v[1]); o.y = pk2e(v[2], v[3]); *(u32x2*)p = o; }
; DI void st_tr4(bf16_t* p, size_t stride, f32x4 v) { p[0] = f2bf(v[0]); p[stride] = f2bf(v[1]); p[2 * stride] = f2bf(v[2]); p[3 * stride] = f2bf(v[3]); }
;     ...
;       for (int m = 0; m < 4; ++m) {
;         const int row = brow + ai * HALF + wr * 64 + m * 16 + fr_e;
;         const float rsc = epi.rowscale(row);
;         float ssq = 0.f;
; #pragma unroll
;         for (int bj = 0; bj < 2; ++bj)
;           ssq += epi(row, bcol + bj * HALF + wc * 32, fq_e, acc[ai][bj][m][0] * rsc, acc[ai][bj][m][1] * rsc);
;   DI float rowscale(int row) const { const f32x4 a = *(const f32x4*)(ssp_in + (size_t)row * 8), b = *(const f32x4*)(ssp_in + (size_t)row * 8 + 4);
;     return rsqrtf((((a[0] + a[1]) + (a[2] + a[3])) + ((b[0] + b[1]) + (b[2] + b[3]))) * (1.f / D_) + EPS_); }
;   DI void one(int row, int c, f32x4 v) const {
;     const int b = row >> 12, t = row & 4095;
;     if (c < 2048) { const int h = c >> 7, d = c & 127; st_bf16x4((bf16_t*)(ws + O_NQ) + ((size_t)(b * 16 + h) * T_ + t) * 128 + d, v); }
;     else if (c < 5120) {
;       const int seg = (c - 2048) >> 9, cc = (c - 2048) & 511, g = cc >> 7, d = cc & 127;
;       if (seg == 3 || seg == 5) st_tr4((bf16_t*)(ws + (seg == 3 ? O_VST : O_VWT)) + (size_t)(b * 4 + g) * 128 * T_ + (size_t)(t >> 5) * 4096 + d * 32 + ((((t & 31) >> 2) ^ ((d >> 2) & 7)) << 2) + (t & 3), 32, v);
;       else { const size_t off = seg == 0 ? O_KC : seg == 1 ? O_VC : seg == 2 ? O_KS : O_KW;
;         st_bf16x4((bf16_t*)(ws + off) + ((size_t)(b * 4 + g) * T_ + t) * 128 + d, v); }
;     } else if (c < 5168) { *(f32x4*)((float*)(ws + O_GT) + (size_t)row * 48 + (c - 5120)) = v; }
.LBB0_656:
	s_or_b64 exec, exec, s[0:1]
	v_or_b32_e32 v89, 48, v149
	v_or_b32_e32 v86, s9, v89
	v_ashrrev_i32_e32 v87, 31, v86
	v_readlane_b32 s0, v253, 52
	v_lshlrev_b64 v[82:83], 5, v[86:87]
	v_readlane_b32 s1, v253, 53
	v_bitop3_b32 v88, v89, v155, 28 bitop3:0x6c
	s_nop 0
	v_lshl_add_u64 v[90:91], s[0:1], 0, v[82:83]
	s_nop 0
	v_readlane_b32 s0, v253, 48
	v_readlane_b32 s1, v253, 49
	s_waitcnt vmcnt(8)
	v_mov_b32_e32 v94, v200
	v_mov_b32_e32 v95, v204
	v_mov_b32_e32 v204, v201
	v_pk_add_f32 v[200:201], v[94:95], v[204:205]
	v_mov_b32_e32 v204, v202
	v_mov_b32_e32 v205, v206
	v_mov_b32_e32 v206, v203
	v_pk_add_f32 v[202:203], v[204:205], v[206:207]
	s_nop 0
	v_pk_add_f32 v[200:201], v[200:201], v[202:203]
	v_mov_b64_e32 v[84:85], s[0:1]
	v_add_f32_e32 v0, v200, v201
	v_fmamk_f32 v0, v0, 0x3a000000, v249
	v_cmp_gt_f32_e32 vcc, s84, v0
	v_mul_f32_e32 v82, 0x4b800000, v0
	v_lshlrev_b32_e32 v83, 7, v86
	v_cndmask_b32_e32 v0, v0, v82, vcc
	v_rsq_f32_e32 v0, v0
	v_mad_i64_i32 v[84:85], s[0:1], v86, s75, v[84:85]
	v_and_b32_e32 v90, 0x7f000, v83
	v_mul_f32_e32 v82, 0x45800000, v0
	v_cndmask_b32_e32 v82, v0, v82, vcc
	v_and_b32_e32 v0, 0x7ff80, v83
	v_pk_mul_f32 v[80:81], v[80:81], v[82:83] op_sel_hi:[1,0]
	v_pk_mul_f32 v[78:79], v[78:79], v[82:83] op_sel_hi:[1,0]
	s_and_saveexec_b64 s[0:1], s[38:39]
	s_xor_b64 s[10:11], exec, s[0:1]
	s_cbranch_execz .LBB0_671
	s_cmpk_lt_u32 s8, 0x1400
	s_mov_b64 s[0:1], -1
	s_cbranch_scc1 .LBB0_661
	s_movk_i32 s0, 0x1430
	v_cmp_gt_u32_e32 vcc, s0, v134
	s_and_saveexec_b64 s[0:1], vcc
	s_cbranch_execz .LBB0_660
	v_mov_b32_e32 v135, v1
	v_lshl_add_u64 v[86:87], v[134:135], 2, v[84:85]
	v_add_co_u32_e32 v86, vcc, 0x2a160000, v86
	s_nop 1
	v_addc_co_u32_e32 v87, vcc, 0, v87, vcc
	global_store_dwordx4 v[86:87], v[78:81], off

; DI void st_bf16x4(bf16_t* p, f32x4 v) { u32x2 o; o.x = pk2e(v[0], v[1]); o.y = pk2e(v[2], v[3]); *(u32x2*)p = o; }
; DI void st_tr4(bf16_t* p, size_t stride, f32x4 v) { p[0] = f2bf(v[0]); p[stride] = f2bf(v[1]); p[2 * stride] = f2bf(v[2]); p[3 * stride] = f2bf(v[3]); }
;     ...
;       for (int m = 0; m < 4; ++m) {
;         const int row = brow + ai * HALF + wr * 64 + m * 16 + fr_e;
;         const float rsc = epi.rowscale(row);
;         float ssq = 0.f;
; #pragma unroll
;         for (int bj = 0; bj < 2; ++bj)
;           ssq += epi(row, bcol + bj * HALF + wc * 32, fq_e, acc[ai][bj][m][0] * rsc, acc[ai][bj][m][1] * rsc);
;   DI float rowscale(int row) const { const f32x4 a = *(const f32x4*)(ssp_in + (size_t)row * 8), b = *(const f32x4*)(ssp_in + (size_t)row * 8 + 4);
;     return rsqrtf((((a[0] + a[1]) + (a[2] + a[3])) + ((b[0] + b[1]) + (b[2] + b[3]))) * (1.f / D_) + EPS_); }
;   DI void one(int row, int c, f32x4 v) const {
;     const int b = row >> 12, t = row & 4095;
;     if (c < 2048) { const int h = c >> 7, d = c & 127; st_bf16x4((bf16_t*)(ws + O_NQ) + ((size_t)(b * 16 + h) * T_ + t) * 128 + d, v); }
;     else if (c < 5120) {
;       const int seg = (c - 2048) >> 9, cc = (c - 2048) & 511, g = cc >> 7, d = cc & 127;
;       if (seg == 3 || seg == 5) st_tr4((bf16_t*)(ws + (seg == 3 ? O_VST : O_VWT)) + (size_t)(b * 4 + g) * 128 * T_ + (size_t)(t >> 5) * 4096 + d * 32 + ((((t & 31) >> 2) ^ ((d >> 2) & 7)) << 2) + (t & 3), 32, v);
;       else { const size_t off = seg == 0 ? O_KC : seg == 1 ? O_VC : seg == 2 ? O_KS : O_KW;
;         st_bf16x4((bf16_t*)(ws + off) + ((size_t)(b * 4 + g) * T_ + t) * 128 + d, v); }
;     } else if (c < 5168) { *(f32x4*)((float*)(ws + O_GT) + (size_t)row * 48 + (c - 5120)) = v; }
.LBB0_724:
	s_or_b64 exec, exec, s[0:1]
	s_add_i32 s30, s9, 0x80
	v_or_b32_e32 v74, s30, v149
	v_ashrrev_i32_e32 v75, 31, v74
	v_readlane_b32 s0, v253, 52
	v_lshlrev_b64 v[66:67], 5, v[74:75]
	v_readlane_b32 s1, v253, 53
	s_ashr_i32 s9, s30, 12
	s_lshl_b32 s29, s9, 2
	v_lshl_add_u64 v[70:71], s[0:1], 0, v[66:67]
	s_nop 0
	v_readlane_b32 s0, v253, 48
	v_readlane_b32 s1, v253, 49
	s_waitcnt vmcnt(6)
	v_mov_b32_e32 v76, v208
	v_mov_b32_e32 v77, v212
	v_mov_b32_e32 v212, v209
	v_pk_add_f32 v[208:209], v[76:77], v[212:213]
	v_mov_b32_e32 v212, v210
	v_mov_b32_e32 v213, v214
	v_mov_b32_e32 v214, v211
	v_pk_add_f32 v[210:211], v[212:213], v[214:215]
	s_nop 0
	v_pk_add_f32 v[208:209], v[208:209], v[210:211]
	v_mov_b64_e32 v[68:69], s[0:1]
	v_add_f32_e32 v0, v208, v209
	v_fmamk_f32 v0, v0, 0x3a000000, v249
	v_cmp_gt_f32_e32 vcc, s84, v0
	v_mul_f32_e32 v66, 0x4b800000, v0
	v_lshlrev_b32_e32 v67, 7, v74
	v_cndmask_b32_e32 v0, v0, v66, vcc
	v_rsq_f32_e32 v0, v0
	v_mad_i64_i32 v[68:69], s[0:1], v74, s75, v[68:69]
	v_and_b32_e32 v72, 0x7e000, v67
	v_mul_f32_e32 v66, 0x45800000, v0
	v_cndmask_b32_e32 v66, v0, v66, vcc
	v_and_b32_e32 v0, 0x7e780, v67
	v_pk_mul_f32 v[64:65], v[64:65], v[66:67] op_sel_hi:[1,0]
	v_pk_mul_f32 v[62:63], v[62:63], v[66:67] op_sel_hi:[1,0]
	s_and_saveexec_b64 s[0:1], s[38:39]
	s_xor_b64 s[10:11], exec, s[0:1]
	s_cbranch_execz .LBB0_739
	s_cmpk_lt_u32 s8, 0x1400
	s_mov_b64 s[0:1], -1
	s_cbranch_scc1 .LBB0_729
	s_movk_i32 s0, 0x1430
	v_cmp_gt_u32_e32 vcc, s0, v134
	s_and_saveexec_b64 s[0:1], vcc
	s_cbranch_execz .LBB0_728
	v_mov_b32_e32 v135, v1
	v_lshl_add_u64 v[70:71], v[134:135], 2, v[68:69]
	v_add_co_u32_e32 v70, vcc, 0x2a160000, v70
	s_nop 1
	v_addc_co_u32_e32 v71, vcc, 0, v71, vcc
	global_store_dwordx4 v[70:71], v[62:65], off

; DI void st_bf16x4(bf16_t* p, f32x4 v) { u32x2 o; o.x = pk2e(v[0], v[1]); o.y = pk2e(v[2], v[3]); *(u32x2*)p = o; }
; DI void st_tr4(bf16_t* p, size_t stride, f32x4 v) { p[0] = f2bf(v[0]); p[stride] = f2bf(v[1]); p[2 * stride] = f2bf(v[2]); p[3 * stride] = f2bf(v[3]); }
;     ...
;       for (int m = 0; m < 4; ++m) {
;         const int row = brow + ai * HALF + wr * 64 + m * 16 + fr_e;
;         const float rsc = epi.rowscale(row);
;         float ssq = 0.f;
; #pragma unroll
;         for (int bj = 0; bj < 2; ++bj)
;           ssq += epi(row, bcol + bj * HALF + wc * 32, fq_e, acc[ai][bj][m][0] * rsc, acc[ai][bj][m][1] * rsc);
;   DI float rowscale(int row) const { const f32x4 a = *(const f32x4*)(ssp_in + (size_t)row * 8), b = *(const f32x4*)(ssp_in + (size_t)row * 8 + 4);
;     return rsqrtf((((a[0] + a[1]) + (a[2] + a[3])) + ((b[0] + b[1]) + (b[2] + b[3]))) * (1.f / D_) + EPS_); }
;   DI void one(int row, int c, f32x4 v) const {
;     const int b = row >> 12, t = row & 4095;
;     if (c < 2048) { const int h = c >> 7, d = c & 127; st_bf16x4((bf16_t*)(ws + O_NQ) + ((size_t)(b * 16 + h) * T_ + t) * 128 + d, v); }
;     else if (c < 5120) {
;       const int seg = (c - 2048) >> 9, cc = (c - 2048) & 511, g = cc >> 7, d = cc & 127;
;       if (seg == 3 || seg == 5) st_tr4((bf16_t*)(ws + (seg == 3 ? O_VST : O_VWT)) + (size_t)(b * 4 + g) * 128 * T_ + (size_t)(t >> 5) * 4096 + d * 32 + ((((t & 31) >> 2) ^ ((d >> 2) & 7)) << 2) + (t & 3), 32, v);
;       else { const size_t off = seg == 0 ? O_KC : seg == 1 ? O_VC : seg == 2 ? O_KS : O_KW;
;         st_bf16x4((bf16_t*)(ws + off) + ((size_t)(b * 4 + g) * T_ + t) * 128 + d, v); }
;     } else if (c < 5168) { *(f32x4*)((float*)(ws + O_GT) + (size_t)row * 48 + (c - 5120)) = v; }
.LBB0_792:
	s_or_b64 exec, exec, s[0:1]
	v_or_b32_e32 v60, s30, v141
	v_ashrrev_i32_e32 v61, 31, v60
	v_readlane_b32 s0, v253, 52
	v_lshlrev_b64 v[50:51], 5, v[60:61]
	v_readlane_b32 s1, v253, 53
	s_nop 1
	v_lshl_add_u64 v[54:55], s[0:1], 0, v[50:51]
	s_nop 0
	v_readlane_b32 s0, v253, 48
	v_readlane_b32 s1, v253, 49
	s_waitcnt vmcnt(4)
	v_mov_b32_e32 v62, v216
	v_mov_b32_e32 v63, v220
	v_mov_b32_e32 v220, v217
	v_pk_add_f32 v[216:217], v[62:63], v[220:221]
	v_mov_b32_e32 v220, v218
	v_mov_b32_e32 v221, v222
	v_mov_b32_e32 v222, v219
	v_pk_add_f32 v[218:219], v[220:221], v[222:223]
	s_nop 0
	v_pk_add_f32 v[216:217], v[216:217], v[218:219]
	v_mov_b64_e32 v[52:53], s[0:1]
	v_add_f32_e32 v0, v216, v217
	v_fmamk_f32 v0, v0, 0x3a000000, v249
	v_cmp_gt_f32_e32 vcc, s84, v0
	v_mul_f32_e32 v50, 0x4b800000, v0
	v_lshlrev_b32_e32 v51, 7, v60
	v_cndmask_b32_e32 v0, v0, v50, vcc
	v_rsq_f32_e32 v0, v0
	v_mad_i64_i32 v[52:53], s[0:1], v60, s75, v[52:53]
	v_and_b32_e32 v56, 0x7e000, v51
	v_mul_f32_e32 v50, 0x45800000, v0
	v_cndmask_b32_e32 v50, v0, v50, vcc
	v_and_b32_e32 v0, 0x7ef80, v51
	v_pk_mul_f32 v[48:49], v[48:49], v[50:51] op_sel_hi:[1,0]
	v_pk_mul_f32 v[46:47], v[46:47], v[50:51] op_sel_hi:[1,0]
	s_and_saveexec_b64 s[0:1], s[38:39]
	s_xor_b64 s[10:11], exec, s[0:1]
	s_cbranch_execz .LBB0_807
	s_cmpk_lt_u32 s8, 0x1400
	s_mov_b64 s[0:1], -1
	s_cbranch_scc1 .LBB0_797
	s_movk_i32 s0, 0x1430
	v_cmp_gt_u32_e32 vcc, s0, v134
	s_and_saveexec_b64 s[0:1], vcc
	s_cbranch_execz .LBB0_796
	v_mov_b32_e32 v135, v1
	v_lshl_add_u64 v[54:55], v[134:135], 2, v[52:53]
	v_add_co_u32_e32 v54, vcc, 0x2a160000, v54
	s_nop 1
	v_addc_co_u32_e32 v55, vcc, 0, v55, vcc
	global_store_dwordx4 v[54:55], v[46:49], off

; DI void st_bf16x4(bf16_t* p, f32x4 v) { u32x2 o; o.x = pk2e(v[0], v[1]); o.y = pk2e(v[2], v[3]); *(u32x2*)p = o; }
; DI void st_tr4(bf16_t* p, size_t stride, f32x4 v) { p[0] = f2bf(v[0]); p[stride] = f2bf(v[1]); p[2 * stride] = f2bf(v[2]); p[3 * stride] = f2bf(v[3]); }
;     ...
;       for (int m = 0; m < 4; ++m) {
;         const int row = brow + ai * HALF + wr * 64 + m * 16 + fr_e;
;         const float rsc = epi.rowscale(row);
;         float ssq = 0.f;
; #pragma unroll
;         for (int bj = 0; bj < 2; ++bj)
;           ssq += epi(row, bcol + bj * HALF + wc * 32, fq_e, acc[ai][bj][m][0] * rsc, acc[ai][bj][m][1] * rsc);
;   DI float rowscale(int row) const { const f32x4 a = *(const f32x4*)(ssp_in + (size_t)row * 8), b = *(const f32x4*)(ssp_in + (size_t)row * 8 + 4);
;     return rsqrtf((((a[0] + a[1]) + (a[2] + a[3])) + ((b[0] + b[1]) + (b[2] + b[3]))) * (1.f / D_) + EPS_); }
;   DI void one(int row, int c, f32x4 v) const {
;     const int b = row >> 12, t = row & 4095;
;     if (c < 2048) { const int h = c >> 7, d = c & 127; st_bf16x4((bf16_t*)(ws + O_NQ) + ((size_t)(b * 16 + h) * T_ + t) * 128 + d, v); }
;     else if (c < 5120) {
;       const int seg = (c - 2048) >> 9, cc = (c - 2048) & 511, g = cc >> 7, d = cc & 127;
;       if (seg == 3 || seg == 5) st_tr4((bf16_t*)(ws + (seg == 3 ? O_VST : O_VWT)) + (size_t)(b * 4 + g) * 128 * T_ + (size_t)(t >> 5) * 4096 + d * 32 + ((((t & 31) >> 2) ^ ((d >> 2) & 7)) << 2) + (t & 3), 32, v);
;       else { const size_t off = seg == 0 ? O_KC : seg == 1 ? O_VC : seg == 2 ? O_KS : O_KW;
;         st_bf16x4((bf16_t*)(ws + off) + ((size_t)(b * 4 + g) * T_ + t) * 128 + d, v); }
;     } else if (c < 5168) { *(f32x4*)((float*)(ws + O_GT) + (size_t)row * 48 + (c - 5120)) = v; }
.LBB0_860:
	s_or_b64 exec, exec, s[0:1]
	v_or_b32_e32 v42, s30, v104
	v_ashrrev_i32_e32 v43, 31, v42
	v_readlane_b32 s0, v253, 52
	v_lshlrev_b64 v[34:35], 5, v[42:43]
	v_readlane_b32 s1, v253, 53
	s_nop 1
	v_lshl_add_u64 v[38:39], s[0:1], 0, v[34:35]
	s_nop 0
	v_readlane_b32 s0, v253, 48
	v_readlane_b32 s1, v253, 49
	s_waitcnt vmcnt(2)
	v_mov_b32_e32 v44, v224
	v_mov_b32_e32 v45, v228
	v_mov_b32_e32 v228, v225
	v_pk_add_f32 v[224:225], v[44:45], v[228:229]
	v_mov_b32_e32 v228, v226
	v_mov_b32_e32 v229, v230
	v_mov_b32_e32 v230, v227
	v_pk_add_f32 v[226:227], v[228:229], v[230:231]
	s_nop 0
	v_pk_add_f32 v[224:225], v[224:225], v[226:227]
	v_mov_b64_e32 v[36:37], s[0:1]
	v_add_f32_e32 v0, v224, v225
	v_fmamk_f32 v0, v0, 0x3a000000, v249
	v_cmp_gt_f32_e32 vcc, s84, v0
	v_mul_f32_e32 v34, 0x4b800000, v0
	v_lshlrev_b32_e32 v35, 7, v42
	v_cndmask_b32_e32 v0, v0, v34, vcc
	v_rsq_f32_e32 v0, v0
	v_mad_i64_i32 v[36:37], s[0:1], v42, s75, v[36:37]
	v_and_b32_e32 v40, 0x7f000, v35
	v_mul_f32_e32 v34, 0x45800000, v0
	v_cndmask_b32_e32 v34, v0, v34, vcc
	v_and_b32_e32 v0, 0x7f780, v35
	v_pk_mul_f32 v[32:33], v[32:33], v[34:35] op_sel_hi:[1,0]
	v_pk_mul_f32 v[30:31], v[30:31], v[34:35] op_sel_hi:[1,0]
	s_and_saveexec_b64 s[0:1], s[38:39]
	s_xor_b64 s[10:11], exec, s[0:1]
	s_cbranch_execz .LBB0_875
	s_cmpk_lt_u32 s8, 0x1400
	s_mov_b64 s[0:1], -1
	s_cbranch_scc1 .LBB0_865
	s_movk_i32 s0, 0x1430
	v_cmp_gt_u32_e32 vcc, s0, v134
	s_and_saveexec_b64 s[0:1], vcc
	s_cbranch_execz .LBB0_864
	v_mov_b32_e32 v135, v1
	v_lshl_add_u64 v[38:39], v[134:135], 2, v[36:37]
	v_add_co_u32_e32 v38, vcc, 0x2a160000, v38
	s_nop 1
	v_addc_co_u32_e32 v39, vcc, 0, v39, vcc
	global_store_dwordx4 v[38:39], v[30:33], off

; DI void st_bf16x4(bf16_t* p, f32x4 v) { u32x2 o; o.x = pk2e(v[0], v[1]); o.y = pk2e(v[2], v[3]); *(u32x2*)p = o; }
; DI void st_tr4(bf16_t* p, size_t stride, f32x4 v) { p[0] = f2bf(v[0]); p[stride] = f2bf(v[1]); p[2 * stride] = f2bf(v[2]); p[3 * stride] = f2bf(v[3]); }
;     ...
;       for (int m = 0; m < 4; ++m) {
;         const int row = brow + ai * HALF + wr * 64 + m * 16 + fr_e;
;         const float rsc = epi.rowscale(row);
;         float ssq = 0.f;
; #pragma unroll
;         for (int bj = 0; bj < 2; ++bj)
;           ssq += epi(row, bcol + bj * HALF + wc * 32, fq_e, acc[ai][bj][m][0] * rsc, acc[ai][bj][m][1] * rsc);
;   DI float rowscale(int row) const { const f32x4 a = *(const f32x4*)(ssp_in + (size_t)row * 8), b = *(const f32x4*)(ssp_in + (size_t)row * 8 + 4);
;     return rsqrtf((((a[0] + a[1]) + (a[2] + a[3])) + ((b[0] + b[1]) + (b[2] + b[3]))) * (1.f / D_) + EPS_); }
;   DI void one(int row, int c, f32x4 v) const {
;     const int b = row >> 12, t = row & 4095;
;     if (c < 2048) { const int h = c >> 7, d = c & 127; st_bf16x4((bf16_t*)(ws + O_NQ) + ((size_t)(b * 16 + h) * T_ + t) * 128 + d, v); }
;     else if (c < 5120) {
;       const int seg = (c - 2048) >> 9, cc = (c - 2048) & 511, g = cc >> 7, d = cc & 127;
;       if (seg == 3 || seg == 5) st_tr4((bf16_t*)(ws + (seg == 3 ? O_VST : O_VWT)) + (size_t)(b * 4 + g) * 128 * T_ + (size_t)(t >> 5) * 4096 + d * 32 + ((((t & 31) >> 2) ^ ((d >> 2) & 7)) << 2) + (t & 3), 32, v);
;       else { const size_t off = seg == 0 ? O_KC : seg == 1 ? O_VC : seg == 2 ? O_KS : O_KW;
;         st_bf16x4((bf16_t*)(ws + off) + ((size_t)(b * 4 + g) * T_ + t) * 128 + d, v); }
;     } else if (c < 5168) { *(f32x4*)((float*)(ws + O_GT) + (size_t)row * 48 + (c - 5120)) = v; }
.LBB0_928:
	s_or_b64 exec, exec, s[0:1]
	v_or_b32_e32 v26, s30, v89
	v_ashrrev_i32_e32 v27, 31, v26
	v_readlane_b32 s0, v253, 52
	v_lshlrev_b64 v[18:19], 5, v[26:27]
	v_readlane_b32 s1, v253, 53
	s_nop 1
	v_lshl_add_u64 v[22:23], s[0:1], 0, v[18:19]
	s_nop 0
	v_readlane_b32 s0, v253, 48
	v_readlane_b32 s1, v253, 49
	s_waitcnt vmcnt(0)
	v_mov_b32_e32 v28, v232
	v_mov_b32_e32 v29, v236
	v_mov_b32_e32 v236, v233
	v_pk_add_f32 v[232:233], v[28:29], v[236:237]
	v_mov_b32_e32 v236, v234
	v_mov_b32_e32 v237, v238
	v_mov_b32_e32 v238, v235
	v_pk_add_f32 v[234:235], v[236:237], v[238:239]
	s_nop 0
	v_pk_add_f32 v[232:233], v[232:233], v[234:235]
	v_mov_b64_e32 v[20:21], s[0:1]
	v_add_f32_e32 v0, v232, v233
	v_fmamk_f32 v0, v0, 0x3a000000, v249
	v_cmp_gt_f32_e32 vcc, s84, v0
	v_mul_f32_e32 v18, 0x4b800000, v0
	v_lshlrev_b32_e32 v19, 7, v26
	v_cndmask_b32_e32 v0, v0, v18, vcc
	v_rsq_f32_e32 v0, v0
	v_mad_i64_i32 v[20:21], s[0:1], v26, s75, v[20:21]
	v_and_b32_e32 v24, 0x7f000, v19
	v_mul_f32_e32 v18, 0x45800000, v0
	v_cndmask_b32_e32 v18, v0, v18, vcc
	v_and_b32_e32 v0, 0x7ff80, v19
	v_pk_mul_f32 v[16:17], v[16:17], v[18:19] op_sel_hi:[1,0]
	v_pk_mul_f32 v[14:15], v[14:15], v[18:19] op_sel_hi:[1,0]
	s_and_saveexec_b64 s[0:1], s[38:39]
	s_xor_b64 s[10:11], exec, s[0:1]
	s_cbranch_execz .LBB0_943
	s_cmpk_lt_u32 s8, 0x1400
	s_mov_b64 s[0:1], -1
	s_cbranch_scc1 .LBB0_933
	s_movk_i32 s0, 0x1430
	v_cmp_gt_u32_e32 vcc, s0, v134
	s_and_saveexec_b64 s[0:1], vcc
	s_cbranch_execz .LBB0_932
	v_mov_b32_e32 v135, v1
	v_lshl_add_u64 v[22:23], v[134:135], 2, v[20:21]
	v_add_co_u32_e32 v22, vcc, 0x2a160000, v22
	s_nop 1
	v_addc_co_u32_e32 v23, vcc, 0, v23, vcc
	global_store_dwordx4 v[22:23], v[14:17], off

; DI void st_bf16x4(bf16_t* p, f32x4 v) { u32x2 o; o.x = pk2e(v[0], v[1]); o.y = pk2e(v[2], v[3]); *(u32x2*)p = o; }
; DI void st_tr4(bf16_t* p, size_t stride, f32x4 v) { p[0] = f2bf(v[0]); p[stride] = f2bf(v[1]); p[2 * stride] = f2bf(v[2]); p[3 * stride] = f2bf(v[3]); }
;     ...
;       for (int m = 0; m < 4; ++m) {
;         const int row = brow + ai * HALF + wr * 64 + m * 16 + fr_e;
;         const float rsc = epi.rowscale(row);
;         float ssq = 0.f;
; #pragma unroll
;         for (int bj = 0; bj < 2; ++bj)
;           ssq += epi(row, bcol + bj * HALF + wc * 32, fq_e, acc[ai][bj][m][0] * rsc, acc[ai][bj][m][1] * rsc);
;   DI float rowscale(int row) const { const f32x4 a = *(const f32x4*)(ssp_in + (size_t)row * 8), b = *(const f32x4*)(ssp_in + (size_t)row * 8 + 4);
;     return rsqrtf((((a[0] + a[1]) + (a[2] + a[3])) + ((b[0] + b[1]) + (b[2] + b[3]))) * (1.f / D_) + EPS_); }
;   DI void one(int row, int c, f32x4 v) const {
;     const int b = row >> 12, t = row & 4095;
;     if (c < 3072) {
;       const int seg = c >> 10, cc = c & 1023, h = cc >> 7, d = cc & 127;
;       if (seg < 2) st_bf16x4((bf16_t*)(ws + (seg == 0 ? E_FQ : E_FK)) + ((size_t)(b * 8 + h) * T_ + t) * 128 + d, v);
;       else st_tr4((bf16_t*)(ws + E_FVT) + (size_t)(b * 8 + h) * 128 * T_ + (size_t)(t >> 5) * 4096 + d * 32 + ((((t & 31) >> 2) ^ ((d >> 2) & 7)) << 2) + (t & 3), 32, v);
;     } else if (c < 4096) { st_bf16x4((bf16_t*)(ws + E_HQ) + (size_t)row * 1024 + (c - 3072), v);
;     } else if (c < 5120) { *(f32x4*)((float*)(ws + E_HF) + (size_t)row * 1024 + (c - 4096)) = v;
;     } else if (c < 6144) { const int cc = c - 5120, h = cc >> 7, d = cc & 127; st_tr4((bf16_t*)(ws + E_HIT) + (size_t)(b * 8 + h) * 128 * T_ + (size_t)(t >> 5) * 4096 + d * 32 + (t & 31), 32, v);
;     } else if (c < 7168) { st_bf16x4((bf16_t*)(ws + E_HG) + (size_t)row * 1024 + (c - 6144), v);
;     } else if (c < 7176) { *(f32x4*)((float*)(ws + E_FF) + (size_t)row * 8 + (c - 7168)) = v; }
.LBB0_1008:
	v_mov_b32_e32 v143, v199
	s_add_i32 s9, s10, s22
	v_and_b32_e32 v151, 15, v143
	s_ashr_i32 s10, s9, 9
	v_or_b32_e32 v146, s9, v151
	s_and_b32 s18, s10, -8
	v_ashrrev_i32_e32 v147, 31, v146
	v_readlane_b32 s10, v253, 52
	v_lshlrev_b64 v[144:145], 5, v[146:147]
	v_readlane_b32 s11, v253, 53
	v_lshrrev_b32_e32 v153, 2, v143
	v_and_b32_e32 v157, 12, v153
	v_lshl_add_u64 v[138:139], s[10:11], 0, v[144:145]
	s_mov_b64 s[100:101], 0x1000
	v_lshl_add_u64 v[240:241], v[138:139], 0, s[100:101]
	global_load_dwordx4 v[162:165], v[240:241], off offset:-4096
	global_load_dwordx4 v[166:169], v[240:241], off offset:-4080
	global_load_dwordx4 v[170:173], v[240:241], off offset:-3584
	global_load_dwordx4 v[174:177], v[240:241], off offset:-3568
	global_load_dwordx4 v[178:181], v[240:241], off offset:-3072
	global_load_dwordx4 v[182:185], v[240:241], off offset:-3056
	global_load_dwordx4 v[200:203], v[240:241], off offset:-2560
	global_load_dwordx4 v[204:207], v[240:241], off offset:-2544
	global_load_dwordx4 v[208:211], v[240:241], off
	global_load_dwordx4 v[212:215], v[240:241], off offset:16
	global_load_dwordx4 v[216:219], v[240:241], off offset:512
	global_load_dwordx4 v[220:223], v[240:241], off offset:528
	global_load_dwordx4 v[224:227], v[240:241], off offset:1024
	global_load_dwordx4 v[228:231], v[240:241], off offset:1040
	global_load_dwordx4 v[232:235], v[240:241], off offset:1536
	global_load_dwordx4 v[236:239], v[240:241], off offset:1552
	s_nop 0
	v_readlane_b32 s10, v253, 48
	v_readlane_b32 s11, v253, 49
	v_or_b32_e32 v150, s8, v157
	s_movk_i32 s14, 0xbff
	s_waitcnt vmcnt(14)
	v_mov_b32_e32 v154, v162
	v_mov_b32_e32 v155, v166
	v_mov_b32_e32 v166, v163
	v_pk_add_f32 v[162:163], v[154:155], v[166:167]
	v_mov_b32_e32 v166, v164
	v_mov_b32_e32 v167, v168
	v_mov_b32_e32 v168, v165
	v_pk_add_f32 v[164:165], v[166:167], v[168:169]
	v_lshl_add_u64 v[138:139], s[10:11], 0, v[144:145]
	v_pk_add_f32 v[162:163], v[162:163], v[164:165]
	s_movk_i32 s10, 0x7e0
	v_add_f32_e32 v0, v162, v163
	v_fmamk_f32 v0, v0, 0x3a000000, v249
	v_cmp_gt_f32_e32 vcc, s84, v0
	v_mul_f32_e32 v134, 0x4b800000, v0
	v_mad_i64_i32 v[136:137], s[10:11], v146, s10, v[138:139]
	v_cndmask_b32_e32 v0, v0, v134, vcc
	v_rsq_f32_e32 v0, v0
	s_lshl_b32 s10, s9, 8
	s_and_b32 s19, s10, 0xfc000
	s_add_u32 s12, s4, s19
	v_mul_f32_e32 v134, 0x45800000, v0
	v_cndmask_b32_e32 v142, v0, v134, vcc
	s_addc_u32 s13, s5, 0
	v_lshlrev_b64 v[134:135], 11, v[146:147]
	v_lshl_add_u64 v[140:141], v[136:137], 0, v[134:135]
	s_add_u32 s10, s6, s19
	v_or_b32_e32 v134, s23, v150
	v_mov_b64_e32 v[144:145], s[12:13]
	s_addc_u32 s11, s7, 0
	v_pk_mul_f32 v[128:129], v[128:129], v[142:143] op_sel_hi:[1,0]
	v_pk_mul_f32 v[126:127], v[126:127], v[142:143] op_sel_hi:[1,0]
	v_cmp_lt_i32_e64 s[40:41], s14, v134
	s_and_saveexec_b64 s[14:15], s[40:41]
	s_xor_b64 s[14:15], exec, s[14:15]
	s_cbranch_execz .LBB0_1027
	s_cmpk_gt_u32 s8, 0xfff
	s_mov_b64 s[16:17], -1
	s_cbranch_scc0 .LBB0_1025
	s_cmpk_gt_u32 s8, 0x13ff
	s_cbranch_scc0 .LBB0_1022
	s_cmpk_gt_u32 s8, 0x17ff
	s_cbranch_scc0 .LBB0_1019
	s_cmpk_gt_u32 s8, 0x1bff
	s_cbranch_scc0 .LBB0_1016
	s_movk_i32 s16, 0x1c08
	v_cmp_gt_u32_e32 vcc, s16, v134
	s_and_saveexec_b64 s[16:17], vcc
	s_cbranch_execz .LBB0_1015
	v_mov_b32_e32 v135, v1
	v_lshl_add_u64 v[154:155], v[134:135], 2, v[138:139]
	v_add_co_u32_e32 v154, vcc, 0x3513e000, v154
	s_nop 1
	v_addc_co_u32_e32 v155, vcc, 0, v155, vcc
	global_store_dwordx4 v[154:155], v[126:129], off

; DI void st_bf16x4(bf16_t* p, f32x4 v) { u32x2 o; o.x = pk2e(v[0], v[1]); o.y = pk2e(v[2], v[3]); *(u32x2*)p = o; }
; DI void st_tr4(bf16_t* p, size_t stride, f32x4 v) { p[0] = f2bf(v[0]); p[stride] = f2bf(v[1]); p[2 * stride] = f2bf(v[2]); p[3 * stride] = f2bf(v[3]); }
;     ...
;       for (int m = 0; m < 4; ++m) {
;         const int row = brow + ai * HALF + wr * 64 + m * 16 + fr_e;
;         const float rsc = epi.rowscale(row);
;         float ssq = 0.f;
; #pragma unroll
;         for (int bj = 0; bj < 2; ++bj)
;           ssq += epi(row, bcol + bj * HALF + wc * 32, fq_e, acc[ai][bj][m][0] * rsc, acc[ai][bj][m][1] * rsc);
;   DI float rowscale(int row) const { const f32x4 a = *(const f32x4*)(ssp_in + (size_t)row * 8), b = *(const f32x4*)(ssp_in + (size_t)row * 8 + 4);
;     return rsqrtf((((a[0] + a[1]) + (a[2] + a[3])) + ((b[0] + b[1]) + (b[2] + b[3]))) * (1.f / D_) + EPS_); }
;   DI void one(int row, int c, f32x4 v) const {
;     const int b = row >> 12, t = row & 4095;
;     if (c < 3072) {
;       const int seg = c >> 10, cc = c & 1023, h = cc >> 7, d = cc & 127;
;       if (seg < 2) st_bf16x4((bf16_t*)(ws + (seg == 0 ? E_FQ : E_FK)) + ((size_t)(b * 8 + h) * T_ + t) * 128 + d, v);
;       else st_tr4((bf16_t*)(ws + E_FVT) + (size_t)(b * 8 + h) * 128 * T_ + (size_t)(t >> 5) * 4096 + d * 32 + ((((t & 31) >> 2) ^ ((d >> 2) & 7)) << 2) + (t & 3), 32, v);
;     } else if (c < 4096) { st_bf16x4((bf16_t*)(ws + E_HQ) + (size_t)row * 1024 + (c - 3072), v);
;     } else if (c < 5120) { *(f32x4*)((float*)(ws + E_HF) + (size_t)row * 1024 + (c - 4096)) = v;
;     } else if (c < 6144) { const int cc = c - 5120, h = cc >> 7, d = cc & 127; st_tr4((bf16_t*)(ws + E_HIT) + (size_t)(b * 8 + h) * 128 * T_ + (size_t)(t >> 5) * 4096 + d * 32 + (t & 31), 32, v);
;     } else if (c < 7168) { st_bf16x4((bf16_t*)(ws + E_HG) + (size_t)row * 1024 + (c - 6144), v);
;     } else if (c < 7176) { *(f32x4*)((float*)(ws + E_FF) + (size_t)row * 8 + (c - 7168)) = v; }
.LBB0_1108:
	s_or_b64 exec, exec, s[12:13]
	v_or_b32_e32 v138, 16, v151
	v_or_b32_e32 v126, s9, v138
	v_ashrrev_i32_e32 v127, 31, v126
	v_readlane_b32 s10, v253, 52
	v_lshlrev_b64 v[124:125], 5, v[126:127]
	v_readlane_b32 s11, v253, 53
	s_add_u32 s12, s4, s19
	s_addc_u32 s13, s5, 0
	v_lshl_add_u64 v[118:119], s[10:11], 0, v[124:125]
	s_nop 0
	v_readlane_b32 s10, v253, 48
	v_readlane_b32 s11, v253, 49
	s_waitcnt vmcnt(12)
	v_mov_b32_e32 v140, v170
	v_mov_b32_e32 v141, v174
	v_mov_b32_e32 v174, v171
	v_pk_add_f32 v[170:171], v[140:141], v[174:175]
	v_mov_b32_e32 v174, v172
	v_mov_b32_e32 v175, v176
	v_mov_b32_e32 v176, v173
	v_pk_add_f32 v[172:173], v[174:175], v[176:177]
	v_lshlrev_b64 v[118:119], 11, v[126:127]
	v_pk_add_f32 v[170:171], v[170:171], v[172:173]
	v_lshl_add_u64 v[116:117], s[10:11], 0, v[124:125]
	v_add_f32_e32 v0, v170, v171
	v_fmamk_f32 v0, v0, 0x3a000000, v249
	v_cmp_gt_f32_e32 vcc, s84, v0
	v_mul_f32_e32 v114, 0x4b800000, v0
	s_movk_i32 s10, 0x7e0
	v_cndmask_b32_e32 v0, v0, v114, vcc
	v_rsq_f32_e32 v0, v0
	v_mov_b64_e32 v[124:125], s[12:13]
	v_mul_f32_e32 v114, 0x45800000, v0
	v_cndmask_b32_e32 v120, v0, v114, vcc
	v_mad_i64_i32 v[114:115], s[10:11], v126, s10, v[116:117]
	s_add_u32 s10, s6, s19
	v_lshl_add_u64 v[118:119], v[114:115], 0, v[118:119]
	s_addc_u32 s11, s7, 0
	v_pk_mul_f32 v[112:113], v[112:113], v[120:121] op_sel_hi:[1,0]
	v_pk_mul_f32 v[110:111], v[110:111], v[120:121] op_sel_hi:[1,0]
	s_and_saveexec_b64 s[14:15], s[40:41]
	s_xor_b64 s[14:15], exec, s[14:15]
	s_cbranch_execz .LBB0_1127
	s_cmpk_lt_u32 s8, 0x1000
	s_mov_b64 s[16:17], -1
	s_cbranch_scc1 .LBB0_1125
	s_cmpk_lt_u32 s8, 0x1400
	s_cbranch_scc1 .LBB0_1122
	s_cmpk_lt_u32 s8, 0x1800
	s_cbranch_scc1 .LBB0_1119
	s_cmpk_lt_u32 s8, 0x1c00
	s_cbranch_scc1 .LBB0_1116
	s_movk_i32 s16, 0x1c08
	v_cmp_gt_u32_e32 vcc, s16, v134
	s_and_saveexec_b64 s[16:17], vcc
	s_cbranch_execz .LBB0_1115
	v_mov_b32_e32 v135, v1
	v_lshl_add_u64 v[140:141], v[134:135], 2, v[116:117]
	v_add_co_u32_e32 v140, vcc, 0x3513e000, v140
	s_nop 1
	v_addc_co_u32_e32 v141, vcc, 0, v141, vcc
	global_store_dwordx4 v[140:141], v[110:113], off

; DI void st_bf16x4(bf16_t* p, f32x4 v) { u32x2 o; o.x = pk2e(v[0], v[1]); o.y = pk2e(v[2], v[3]); *(u32x2*)p = o; }
; DI void st_tr4(bf16_t* p, size_t stride, f32x4 v) { p[0] = f2bf(v[0]); p[stride] = f2bf(v[1]); p[2 * stride] = f2bf(v[2]); p[3 * stride] = f2bf(v[3]); }
;     ...
;       for (int m = 0; m < 4; ++m) {
;         const int row = brow + ai * HALF + wr * 64 + m * 16 + fr_e;
;         const float rsc = epi.rowscale(row);
;         float ssq = 0.f;
; #pragma unroll
;         for (int bj = 0; bj < 2; ++bj)
;           ssq += epi(row, bcol + bj * HALF + wc * 32, fq_e, acc[ai][bj][m][0] * rsc, acc[ai][bj][m][1] * rsc);
;   DI float rowscale(int row) const { const f32x4 a = *(const f32x4*)(ssp_in + (size_t)row * 8), b = *(const f32x4*)(ssp_in + (size_t)row * 8 + 4);
;     return rsqrtf((((a[0] + a[1]) + (a[2] + a[3])) + ((b[0] + b[1]) + (b[2] + b[3]))) * (1.f / D_) + EPS_); }
;   DI void one(int row, int c, f32x4 v) const {
;     const int b = row >> 12, t = row & 4095;
;     if (c < 3072) {
;       const int seg = c >> 10, cc = c & 1023, h = cc >> 7, d = cc & 127;
;       if (seg < 2) st_bf16x4((bf16_t*)(ws + (seg == 0 ? E_FQ : E_FK)) + ((size_t)(b * 8 + h) * T_ + t) * 128 + d, v);
;       else st_tr4((bf16_t*)(ws + E_FVT) + (size_t)(b * 8 + h) * 128 * T_ + (size_t)(t >> 5) * 4096 + d * 32 + ((((t & 31) >> 2) ^ ((d >> 2) & 7)) << 2) + (t & 3), 32, v);
;     } else if (c < 4096) { st_bf16x4((bf16_t*)(ws + E_HQ) + (size_t)row * 1024 + (c - 3072), v);
;     } else if (c < 5120) { *(f32x4*)((float*)(ws + E_HF) + (size_t)row * 1024 + (c - 4096)) = v;
;     } else if (c < 6144) { const int cc = c - 5120, h = cc >> 7, d = cc & 127; st_tr4((bf16_t*)(ws + E_HIT) + (size_t)(b * 8 + h) * 128 * T_ + (size_t)(t >> 5) * 4096 + d * 32 + (t & 31), 32, v);
;     } else if (c < 7168) { st_bf16x4((bf16_t*)(ws + E_HG) + (size_t)row * 1024 + (c - 6144), v);
;     } else if (c < 7176) { *(f32x4*)((float*)(ws + E_FF) + (size_t)row * 8 + (c - 7168)) = v; }
.LBB0_1208:
	s_or_b64 exec, exec, s[12:13]
	v_or_b32_e32 v110, 32, v151
	v_or_b32_e32 v108, s9, v110
	v_ashrrev_i32_e32 v109, 31, v108
	v_readlane_b32 s10, v253, 52
	v_lshlrev_b64 v[106:107], 5, v[108:109]
	v_readlane_b32 s11, v253, 53
	s_nop 1
	v_lshl_add_u64 v[102:103], s[10:11], 0, v[106:107]
	s_nop 0
	v_readlane_b32 s10, v253, 48
	v_readlane_b32 s11, v253, 49
	s_waitcnt vmcnt(10)
	v_mov_b32_e32 v112, v178
	v_mov_b32_e32 v113, v182
	v_mov_b32_e32 v182, v179
	v_pk_add_f32 v[178:179], v[112:113], v[182:183]
	v_mov_b32_e32 v182, v180
	v_mov_b32_e32 v183, v184
	v_mov_b32_e32 v184, v181
	v_pk_add_f32 v[180:181], v[182:183], v[184:185]
	s_nop 0
	v_pk_add_f32 v[178:179], v[178:179], v[180:181]
	v_lshl_add_u64 v[100:101], s[10:11], 0, v[106:107]
	v_add_f32_e32 v0, v178, v179
	v_fmamk_f32 v0, v0, 0x3a000000, v249
	v_cmp_gt_f32_e32 vcc, s84, v0
	v_mul_f32_e32 v98, 0x4b800000, v0
	s_movk_i32 s10, 0x7e0
	v_cndmask_b32_e32 v0, v0, v98, vcc
	v_rsq_f32_e32 v0, v0
	v_lshlrev_b64 v[106:107], 11, v[108:109]
	v_mul_f32_e32 v98, 0x45800000, v0
	v_cndmask_b32_e32 v104, v0, v98, vcc
	v_lshlrev_b32_e32 v0, 8, v108
	v_mad_i64_i32 v[98:99], s[10:11], v108, s10, v[100:101]
	v_and_b32_e32 v0, 0xfe000, v0
	v_lshl_add_u64 v[102:103], s[4:5], 0, v[0:1]
	v_lshl_add_u64 v[106:107], v[98:99], 0, v[106:107]
	v_pk_mul_f32 v[96:97], v[96:97], v[104:105] op_sel_hi:[1,0]
	v_pk_mul_f32 v[94:95], v[94:95], v[104:105] op_sel_hi:[1,0]
	s_and_saveexec_b64 s[10:11], s[40:41]
	s_xor_b64 s[10:11], exec, s[10:11]
	s_cbranch_execz .LBB0_1227
	s_cmpk_lt_u32 s8, 0x1000
	s_mov_b64 s[12:13], -1
	s_cbranch_scc1 .LBB0_1225
	s_cmpk_lt_u32 s8, 0x1400
	s_cbranch_scc1 .LBB0_1222
	s_cmpk_lt_u32 s8, 0x1800
	s_cbranch_scc1 .LBB0_1219
	s_cmpk_lt_u32 s8, 0x1c00
	s_cbranch_scc1 .LBB0_1216
	s_movk_i32 s12, 0x1c08
	v_cmp_gt_u32_e32 vcc, s12, v134
	s_and_saveexec_b64 s[12:13], vcc
	s_cbranch_execz .LBB0_1215
	v_mov_b32_e32 v135, v1
	v_lshl_add_u64 v[112:113], v[134:135], 2, v[100:101]
	v_add_co_u32_e32 v112, vcc, 0x3513e000, v112
	s_nop 1
	v_addc_co_u32_e32 v113, vcc, 0, v113, vcc
	global_store_dwordx4 v[112:113], v[94:97], off

; DI void st_bf16x4(bf16_t* p, f32x4 v) { u32x2 o; o.x = pk2e(v[0], v[1]); o.y = pk2e(v[2], v[3]); *(u32x2*)p = o; }
; DI void st_tr4(bf16_t* p, size_t stride, f32x4 v) { p[0] = f2bf(v[0]); p[stride] = f2bf(v[1]); p[2 * stride] = f2bf(v[2]); p[3 * stride] = f2bf(v[3]); }
;     ...
;       for (int m = 0; m < 4; ++m) {
;         const int row = brow + ai * HALF + wr * 64 + m * 16 + fr_e;
;         const float rsc = epi.rowscale(row);
;         float ssq = 0.f;
; #pragma unroll
;         for (int bj = 0; bj < 2; ++bj)
;           ssq += epi(row, bcol + bj * HALF + wc * 32, fq_e, acc[ai][bj][m][0] * rsc, acc[ai][bj][m][1] * rsc);
;   DI float rowscale(int row) const { const f32x4 a = *(const f32x4*)(ssp_in + (size_t)row * 8), b = *(const f32x4*)(ssp_in + (size_t)row * 8 + 4);
;     return rsqrtf((((a[0] + a[1]) + (a[2] + a[3])) + ((b[0] + b[1]) + (b[2] + b[3]))) * (1.f / D_) + EPS_); }
;   DI void one(int row, int c, f32x4 v) const {
;     const int b = row >> 12, t = row & 4095;
;     if (c < 3072) {
;       const int seg = c >> 10, cc = c & 1023, h = cc >> 7, d = cc & 127;
;       if (seg < 2) st_bf16x4((bf16_t*)(ws + (seg == 0 ? E_FQ : E_FK)) + ((size_t)(b * 8 + h) * T_ + t) * 128 + d, v);
;       else st_tr4((bf16_t*)(ws + E_FVT) + (size_t)(b * 8 + h) * 128 * T_ + (size_t)(t >> 5) * 4096 + d * 32 + ((((t & 31) >> 2) ^ ((d >> 2) & 7)) << 2) + (t & 3), 32, v);
;     } else if (c < 4096) { st_bf16x4((bf16_t*)(ws + E_HQ) + (size_t)row * 1024 + (c - 3072), v);
;     } else if (c < 5120) { *(f32x4*)((float*)(ws + E_HF) + (size_t)row * 1024 + (c - 4096)) = v;
;     } else if (c < 6144) { const int cc = c - 5120, h = cc >> 7, d = cc & 127; st_tr4((bf16_t*)(ws + E_HIT) + (size_t)(b * 8 + h) * 128 * T_ + (size_t)(t >> 5) * 4096 + d * 32 + (t & 31), 32, v);
;     } else if (c < 7168) { st_bf16x4((bf16_t*)(ws + E_HG) + (size_t)row * 1024 + (c - 6144), v);
;     } else if (c < 7176) { *(f32x4*)((float*)(ws + E_FF) + (size_t)row * 8 + (c - 7168)) = v; }
.LBB0_1308:
	s_or_b64 exec, exec, s[10:11]
	v_or_b32_e32 v95, 48, v151
	v_or_b32_e32 v92, s9, v95
	v_ashrrev_i32_e32 v93, 31, v92
	v_readlane_b32 s10, v253, 52
	v_lshlrev_b64 v[90:91], 5, v[92:93]
	v_readlane_b32 s11, v253, 53
	s_nop 1
	v_lshl_add_u64 v[86:87], s[10:11], 0, v[90:91]
	s_nop 0
	v_readlane_b32 s10, v253, 48
	v_readlane_b32 s11, v253, 49
	s_waitcnt vmcnt(8)
	v_mov_b32_e32 v96, v200
	v_mov_b32_e32 v97, v204
	v_mov_b32_e32 v204, v201
	v_pk_add_f32 v[200:201], v[96:97], v[204:205]
	v_mov_b32_e32 v204, v202
	v_mov_b32_e32 v205, v206
	v_mov_b32_e32 v206, v203
	v_pk_add_f32 v[202:203], v[204:205], v[206:207]
	s_nop 0
	v_pk_add_f32 v[200:201], v[200:201], v[202:203]
	v_lshl_add_u64 v[84:85], s[10:11], 0, v[90:91]
	v_add_f32_e32 v0, v200, v201
	v_fmamk_f32 v0, v0, 0x3a000000, v249
	v_cmp_gt_f32_e32 vcc, s84, v0
	v_mul_f32_e32 v82, 0x4b800000, v0
	s_movk_i32 s10, 0x7e0
	v_cndmask_b32_e32 v0, v0, v82, vcc
	v_rsq_f32_e32 v0, v0
	v_lshlrev_b64 v[90:91], 11, v[92:93]
	v_mul_f32_e32 v82, 0x45800000, v0
	v_cndmask_b32_e32 v88, v0, v82, vcc
	v_lshlrev_b32_e32 v0, 8, v92
	v_mad_i64_i32 v[82:83], s[10:11], v92, s10, v[84:85]
	v_and_b32_e32 v0, 0xfe000, v0
	v_lshl_add_u64 v[86:87], s[4:5], 0, v[0:1]
	v_lshl_add_u64 v[90:91], v[82:83], 0, v[90:91]
	v_pk_mul_f32 v[80:81], v[80:81], v[88:89] op_sel_hi:[1,0]
	v_pk_mul_f32 v[78:79], v[78:79], v[88:89] op_sel_hi:[1,0]
	s_and_saveexec_b64 s[10:11], s[40:41]
	s_xor_b64 s[10:11], exec, s[10:11]
	s_cbranch_execz .LBB0_1327
	s_cmpk_lt_u32 s8, 0x1000
	s_mov_b64 s[12:13], -1
	s_cbranch_scc1 .LBB0_1325
	s_cmpk_lt_u32 s8, 0x1400
	s_cbranch_scc1 .LBB0_1322
	s_cmpk_lt_u32 s8, 0x1800
	s_cbranch_scc1 .LBB0_1319
	s_cmpk_lt_u32 s8, 0x1c00
	s_cbranch_scc1 .LBB0_1316
	s_movk_i32 s12, 0x1c08
	v_cmp_gt_u32_e32 vcc, s12, v134
	s_and_saveexec_b64 s[12:13], vcc
	s_cbranch_execz .LBB0_1315
	v_mov_b32_e32 v135, v1
	v_lshl_add_u64 v[96:97], v[134:135], 2, v[84:85]
	v_add_co_u32_e32 v96, vcc, 0x3513e000, v96
	s_nop 1
	v_addc_co_u32_e32 v97, vcc, 0, v97, vcc
	global_store_dwordx4 v[96:97], v[78:81], off

; DI void st_bf16x4(bf16_t* p, f32x4 v) { u32x2 o; o.x = pk2e(v[0], v[1]); o.y = pk2e(v[2], v[3]); *(u32x2*)p = o; }
; DI void st_tr4(bf16_t* p, size_t stride, f32x4 v) { p[0] = f2bf(v[0]); p[stride] = f2bf(v[1]); p[2 * stride] = f2bf(v[2]); p[3 * stride] = f2bf(v[3]); }
;     ...
;       for (int m = 0; m < 4; ++m) {
;         const int row = brow + ai * HALF + wr * 64 + m * 16 + fr_e;
;         const float rsc = epi.rowscale(row);
;         float ssq = 0.f;
; #pragma unroll
;         for (int bj = 0; bj < 2; ++bj)
;           ssq += epi(row, bcol + bj * HALF + wc * 32, fq_e, acc[ai][bj][m][0] * rsc, acc[ai][bj][m][1] * rsc);
;   DI float rowscale(int row) const { const f32x4 a = *(const f32x4*)(ssp_in + (size_t)row * 8), b = *(const f32x4*)(ssp_in + (size_t)row * 8 + 4);
;     return rsqrtf((((a[0] + a[1]) + (a[2] + a[3])) + ((b[0] + b[1]) + (b[2] + b[3]))) * (1.f / D_) + EPS_); }
;   DI void one(int row, int c, f32x4 v) const {
;     const int b = row >> 12, t = row & 4095;
;     if (c < 3072) {
;       const int seg = c >> 10, cc = c & 1023, h = cc >> 7, d = cc & 127;
;       if (seg < 2) st_bf16x4((bf16_t*)(ws + (seg == 0 ? E_FQ : E_FK)) + ((size_t)(b * 8 + h) * T_ + t) * 128 + d, v);
;       else st_tr4((bf16_t*)(ws + E_FVT) + (size_t)(b * 8 + h) * 128 * T_ + (size_t)(t >> 5) * 4096 + d * 32 + ((((t & 31) >> 2) ^ ((d >> 2) & 7)) << 2) + (t & 3), 32, v);
;     } else if (c < 4096) { st_bf16x4((bf16_t*)(ws + E_HQ) + (size_t)row * 1024 + (c - 3072), v);
;     } else if (c < 5120) { *(f32x4*)((float*)(ws + E_HF) + (size_t)row * 1024 + (c - 4096)) = v;
;     } else if (c < 6144) { const int cc = c - 5120, h = cc >> 7, d = cc & 127; st_tr4((bf16_t*)(ws + E_HIT) + (size_t)(b * 8 + h) * 128 * T_ + (size_t)(t >> 5) * 4096 + d * 32 + (t & 31), 32, v);
;     } else if (c < 7168) { st_bf16x4((bf16_t*)(ws + E_HG) + (size_t)row * 1024 + (c - 6144), v);
;     } else if (c < 7176) { *(f32x4*)((float*)(ws + E_FF) + (size_t)row * 8 + (c - 7168)) = v; }
.LBB0_1408:
	s_or_b64 exec, exec, s[10:11]
	s_add_i32 s18, s9, 0x80
	v_or_b32_e32 v76, s18, v151
	v_ashrrev_i32_e32 v77, 31, v76
	v_readlane_b32 s10, v253, 52
	v_lshlrev_b64 v[74:75], 5, v[76:77]
	v_readlane_b32 s11, v253, 53
	s_ashr_i32 s9, s18, 9
	s_and_b32 s9, s9, -8
	v_lshl_add_u64 v[70:71], s[10:11], 0, v[74:75]
	s_nop 0
	v_readlane_b32 s10, v253, 48
	v_readlane_b32 s11, v253, 49
	s_waitcnt vmcnt(6)
	v_mov_b32_e32 v78, v208
	v_mov_b32_e32 v79, v212
	v_mov_b32_e32 v212, v209
	v_pk_add_f32 v[208:209], v[78:79], v[212:213]
	v_mov_b32_e32 v212, v210
	v_mov_b32_e32 v213, v214
	v_mov_b32_e32 v214, v211
	v_pk_add_f32 v[210:211], v[212:213], v[214:215]
	v_lshlrev_b64 v[70:71], 11, v[76:77]
	v_pk_add_f32 v[208:209], v[208:209], v[210:211]
	v_lshl_add_u64 v[68:69], s[10:11], 0, v[74:75]
	v_add_f32_e32 v0, v208, v209
	v_fmamk_f32 v0, v0, 0x3a000000, v249
	v_cmp_gt_f32_e32 vcc, s84, v0
	v_mul_f32_e32 v66, 0x4b800000, v0
	s_movk_i32 s10, 0x7e0
	v_cndmask_b32_e32 v0, v0, v66, vcc
	v_rsq_f32_e32 v0, v0
	s_nop 0
	v_mul_f32_e32 v66, 0x45800000, v0
	v_cndmask_b32_e32 v72, v0, v66, vcc
	v_mad_i64_i32 v[66:67], s[10:11], v76, s10, v[68:69]
	s_lshl_b32 s10, s18, 8
	s_and_b32 s19, s10, 0xfc000
	s_add_u32 s12, s4, s19
	s_addc_u32 s13, s5, 0
	s_add_u32 s10, s6, s19
	v_mov_b64_e32 v[74:75], s[12:13]
	v_lshl_add_u64 v[70:71], v[66:67], 0, v[70:71]
	s_addc_u32 s11, s7, 0
	v_pk_mul_f32 v[64:65], v[64:65], v[72:73] op_sel_hi:[1,0]
	v_pk_mul_f32 v[62:63], v[62:63], v[72:73] op_sel_hi:[1,0]
	s_and_saveexec_b64 s[14:15], s[40:41]
	s_xor_b64 s[14:15], exec, s[14:15]
	s_cbranch_execz .LBB0_1427
	s_cmpk_lt_u32 s8, 0x1000
	s_mov_b64 s[16:17], -1
	s_cbranch_scc1 .LBB0_1425
	s_cmpk_lt_u32 s8, 0x1400
	s_cbranch_scc1 .LBB0_1422
	s_cmpk_lt_u32 s8, 0x1800
	s_cbranch_scc1 .LBB0_1419
	s_cmpk_lt_u32 s8, 0x1c00
	s_cbranch_scc1 .LBB0_1416
	s_movk_i32 s16, 0x1c08
	v_cmp_gt_u32_e32 vcc, s16, v134
	s_and_saveexec_b64 s[16:17], vcc
	s_cbranch_execz .LBB0_1415
	v_mov_b32_e32 v135, v1
	v_lshl_add_u64 v[78:79], v[134:135], 2, v[68:69]
	v_add_co_u32_e32 v78, vcc, 0x3513e000, v78
	s_nop 1
	v_addc_co_u32_e32 v79, vcc, 0, v79, vcc
	global_store_dwordx4 v[78:79], v[62:65], off

; DI void st_bf16x4(bf16_t* p, f32x4 v) { u32x2 o; o.x = pk2e(v[0], v[1]); o.y = pk2e(v[2], v[3]); *(u32x2*)p = o; }
; DI void st_tr4(bf16_t* p, size_t stride, f32x4 v) { p[0] = f2bf(v[0]); p[stride] = f2bf(v[1]); p[2 * stride] = f2bf(v[2]); p[3 * stride] = f2bf(v[3]); }
;     ...
;       for (int m = 0; m < 4; ++m) {
;         const int row = brow + ai * HALF + wr * 64 + m * 16 + fr_e;
;         const float rsc = epi.rowscale(row);
;         float ssq = 0.f;
; #pragma unroll
;         for (int bj = 0; bj < 2; ++bj)
;           ssq += epi(row, bcol + bj * HALF + wc * 32, fq_e, acc[ai][bj][m][0] * rsc, acc[ai][bj][m][1] * rsc);
;   DI float rowscale(int row) const { const f32x4 a = *(const f32x4*)(ssp_in + (size_t)row * 8), b = *(const f32x4*)(ssp_in + (size_t)row * 8 + 4);
;     return rsqrtf((((a[0] + a[1]) + (a[2] + a[3])) + ((b[0] + b[1]) + (b[2] + b[3]))) * (1.f / D_) + EPS_); }
;   DI void one(int row, int c, f32x4 v) const {
;     const int b = row >> 12, t = row & 4095;
;     if (c < 3072) {
;       const int seg = c >> 10, cc = c & 1023, h = cc >> 7, d = cc & 127;
;       if (seg < 2) st_bf16x4((bf16_t*)(ws + (seg == 0 ? E_FQ : E_FK)) + ((size_t)(b * 8 + h) * T_ + t) * 128 + d, v);
;       else st_tr4((bf16_t*)(ws + E_FVT) + (size_t)(b * 8 + h) * 128 * T_ + (size_t)(t >> 5) * 4096 + d * 32 + ((((t & 31) >> 2) ^ ((d >> 2) & 7)) << 2) + (t & 3), 32, v);
;     } else if (c < 4096) { st_bf16x4((bf16_t*)(ws + E_HQ) + (size_t)row * 1024 + (c - 3072), v);
;     } else if (c < 5120) { *(f32x4*)((float*)(ws + E_HF) + (size_t)row * 1024 + (c - 4096)) = v;
;     } else if (c < 6144) { const int cc = c - 5120, h = cc >> 7, d = cc & 127; st_tr4((bf16_t*)(ws + E_HIT) + (size_t)(b * 8 + h) * 128 * T_ + (size_t)(t >> 5) * 4096 + d * 32 + (t & 31), 32, v);
;     } else if (c < 7168) { st_bf16x4((bf16_t*)(ws + E_HG) + (size_t)row * 1024 + (c - 6144), v);
;     } else if (c < 7176) { *(f32x4*)((float*)(ws + E_FF) + (size_t)row * 8 + (c - 7168)) = v; }
.LBB0_1508:
	s_or_b64 exec, exec, s[12:13]
	v_or_b32_e32 v62, s18, v138
	v_ashrrev_i32_e32 v63, 31, v62
	v_readlane_b32 s10, v253, 52
	v_lshlrev_b64 v[60:61], 5, v[62:63]
	v_readlane_b32 s11, v253, 53
	s_add_u32 s12, s4, s19
	s_addc_u32 s13, s5, 0
	v_lshl_add_u64 v[54:55], s[10:11], 0, v[60:61]
	s_nop 0
	v_readlane_b32 s10, v253, 48
	v_readlane_b32 s11, v253, 49
	s_waitcnt vmcnt(4)
	v_mov_b32_e32 v64, v216
	v_mov_b32_e32 v65, v220
	v_mov_b32_e32 v220, v217
	v_pk_add_f32 v[216:217], v[64:65], v[220:221]
	v_mov_b32_e32 v220, v218
	v_mov_b32_e32 v221, v222
	v_mov_b32_e32 v222, v219
	v_pk_add_f32 v[218:219], v[220:221], v[222:223]
	v_lshlrev_b64 v[54:55], 11, v[62:63]
	v_pk_add_f32 v[216:217], v[216:217], v[218:219]
	v_lshl_add_u64 v[52:53], s[10:11], 0, v[60:61]
	v_add_f32_e32 v0, v216, v217
	v_fmamk_f32 v0, v0, 0x3a000000, v249
	v_cmp_gt_f32_e32 vcc, s84, v0
	v_mul_f32_e32 v50, 0x4b800000, v0
	s_movk_i32 s10, 0x7e0
	v_cndmask_b32_e32 v0, v0, v50, vcc
	v_rsq_f32_e32 v0, v0
	v_mov_b64_e32 v[60:61], s[12:13]
	v_mul_f32_e32 v50, 0x45800000, v0
	v_cndmask_b32_e32 v56, v0, v50, vcc
	v_mad_i64_i32 v[50:51], s[10:11], v62, s10, v[52:53]
	s_add_u32 s10, s6, s19
	v_lshl_add_u64 v[54:55], v[50:51], 0, v[54:55]
	s_addc_u32 s11, s7, 0
	v_pk_mul_f32 v[48:49], v[48:49], v[56:57] op_sel_hi:[1,0]
	v_pk_mul_f32 v[46:47], v[46:47], v[56:57] op_sel_hi:[1,0]
	s_and_saveexec_b64 s[14:15], s[40:41]
	s_xor_b64 s[14:15], exec, s[14:15]
	s_cbranch_execz .LBB0_1527
	s_cmpk_lt_u32 s8, 0x1000
	s_mov_b64 s[16:17], -1
	s_cbranch_scc1 .LBB0_1525
	s_cmpk_lt_u32 s8, 0x1400
	s_cbranch_scc1 .LBB0_1522
	s_cmpk_lt_u32 s8, 0x1800
	s_cbranch_scc1 .LBB0_1519
	s_cmpk_lt_u32 s8, 0x1c00
	s_cbranch_scc1 .LBB0_1516
	s_movk_i32 s16, 0x1c08
	v_cmp_gt_u32_e32 vcc, s16, v134
	s_and_saveexec_b64 s[16:17], vcc
	s_cbranch_execz .LBB0_1515
	v_mov_b32_e32 v135, v1
	v_lshl_add_u64 v[64:65], v[134:135], 2, v[52:53]
	v_add_co_u32_e32 v64, vcc, 0x3513e000, v64
	s_nop 1
	v_addc_co_u32_e32 v65, vcc, 0, v65, vcc
	global_store_dwordx4 v[64:65], v[46:49], off

; DI void st_bf16x4(bf16_t* p, f32x4 v) { u32x2 o; o.x = pk2e(v[0], v[1]); o.y = pk2e(v[2], v[3]); *(u32x2*)p = o; }
; DI void st_tr4(bf16_t* p, size_t stride, f32x4 v) { p[0] = f2bf(v[0]); p[stride] = f2bf(v[1]); p[2 * stride] = f2bf(v[2]); p[3 * stride] = f2bf(v[3]); }
;     ...
;       for (int m = 0; m < 4; ++m) {
;         const int row = brow + ai * HALF + wr * 64 + m * 16 + fr_e;
;         const float rsc = epi.rowscale(row);
;         float ssq = 0.f;
; #pragma unroll
;         for (int bj = 0; bj < 2; ++bj)
;           ssq += epi(row, bcol + bj * HALF + wc * 32, fq_e, acc[ai][bj][m][0] * rsc, acc[ai][bj][m][1] * rsc);
;   DI float rowscale(int row) const { const f32x4 a = *(const f32x4*)(ssp_in + (size_t)row * 8), b = *(const f32x4*)(ssp_in + (size_t)row * 8 + 4);
;     return rsqrtf((((a[0] + a[1]) + (a[2] + a[3])) + ((b[0] + b[1]) + (b[2] + b[3]))) * (1.f / D_) + EPS_); }
;   DI void one(int row, int c, f32x4 v) const {
;     const int b = row >> 12, t = row & 4095;
;     if (c < 3072) {
;       const int seg = c >> 10, cc = c & 1023, h = cc >> 7, d = cc & 127;
;       if (seg < 2) st_bf16x4((bf16_t*)(ws + (seg == 0 ? E_FQ : E_FK)) + ((size_t)(b * 8 + h) * T_ + t) * 128 + d, v);
;       else st_tr4((bf16_t*)(ws + E_FVT) + (size_t)(b * 8 + h) * 128 * T_ + (size_t)(t >> 5) * 4096 + d * 32 + ((((t & 31) >> 2) ^ ((d >> 2) & 7)) << 2) + (t & 3), 32, v);
;     } else if (c < 4096) { st_bf16x4((bf16_t*)(ws + E_HQ) + (size_t)row * 1024 + (c - 3072), v);
;     } else if (c < 5120) { *(f32x4*)((float*)(ws + E_HF) + (size_t)row * 1024 + (c - 4096)) = v;
;     } else if (c < 6144) { const int cc = c - 5120, h = cc >> 7, d = cc & 127; st_tr4((bf16_t*)(ws + E_HIT) + (size_t)(b * 8 + h) * 128 * T_ + (size_t)(t >> 5) * 4096 + d * 32 + (t & 31), 32, v);
;     } else if (c < 7168) { st_bf16x4((bf16_t*)(ws + E_HG) + (size_t)row * 1024 + (c - 6144), v);
;     } else if (c < 7176) { *(f32x4*)((float*)(ws + E_FF) + (size_t)row * 8 + (c - 7168)) = v; }
.LBB0_1608:
	s_or_b64 exec, exec, s[12:13]
	v_or_b32_e32 v44, s18, v110
	v_ashrrev_i32_e32 v45, 31, v44
	v_readlane_b32 s10, v253, 52
	v_lshlrev_b64 v[42:43], 5, v[44:45]
	v_readlane_b32 s11, v253, 53
	s_nop 1
	v_lshl_add_u64 v[38:39], s[10:11], 0, v[42:43]
	s_nop 0
	v_readlane_b32 s10, v253, 48
	v_readlane_b32 s11, v253, 49
	s_waitcnt vmcnt(2)
	v_mov_b32_e32 v46, v224
	v_mov_b32_e32 v47, v228
	v_mov_b32_e32 v228, v225
	v_pk_add_f32 v[224:225], v[46:47], v[228:229]
	v_mov_b32_e32 v228, v226
	v_mov_b32_e32 v229, v230
	v_mov_b32_e32 v230, v227
	v_pk_add_f32 v[226:227], v[228:229], v[230:231]
	s_nop 0
	v_pk_add_f32 v[224:225], v[224:225], v[226:227]
	v_lshl_add_u64 v[36:37], s[10:11], 0, v[42:43]
	v_add_f32_e32 v0, v224, v225
	v_fmamk_f32 v0, v0, 0x3a000000, v249
	v_cmp_gt_f32_e32 vcc, s84, v0
	v_mul_f32_e32 v34, 0x4b800000, v0
	s_movk_i32 s10, 0x7e0
	v_cndmask_b32_e32 v0, v0, v34, vcc
	v_rsq_f32_e32 v0, v0
	v_lshlrev_b64 v[42:43], 11, v[44:45]
	v_mul_f32_e32 v34, 0x45800000, v0
	v_cndmask_b32_e32 v40, v0, v34, vcc
	v_lshlrev_b32_e32 v0, 8, v44
	v_mad_i64_i32 v[34:35], s[10:11], v44, s10, v[36:37]
	v_and_b32_e32 v0, 0xfe000, v0
	v_lshl_add_u64 v[38:39], s[4:5], 0, v[0:1]
	v_lshl_add_u64 v[42:43], v[34:35], 0, v[42:43]
	v_pk_mul_f32 v[32:33], v[32:33], v[40:41] op_sel_hi:[1,0]
	v_pk_mul_f32 v[30:31], v[30:31], v[40:41] op_sel_hi:[1,0]
	s_and_saveexec_b64 s[10:11], s[40:41]
	s_xor_b64 s[10:11], exec, s[10:11]
	s_cbranch_execz .LBB0_1627
	s_cmpk_lt_u32 s8, 0x1000
	s_mov_b64 s[12:13], -1
	s_cbranch_scc1 .LBB0_1625
	s_cmpk_lt_u32 s8, 0x1400
	s_cbranch_scc1 .LBB0_1622
	s_cmpk_lt_u32 s8, 0x1800
	s_cbranch_scc1 .LBB0_1619
	s_cmpk_lt_u32 s8, 0x1c00
	s_cbranch_scc1 .LBB0_1616
	s_movk_i32 s12, 0x1c08
	v_cmp_gt_u32_e32 vcc, s12, v134
	s_and_saveexec_b64 s[12:13], vcc
	s_cbranch_execz .LBB0_1615
	v_mov_b32_e32 v135, v1
	v_lshl_add_u64 v[46:47], v[134:135], 2, v[36:37]
	v_add_co_u32_e32 v46, vcc, 0x3513e000, v46
	s_nop 1
	v_addc_co_u32_e32 v47, vcc, 0, v47, vcc
	global_store_dwordx4 v[46:47], v[30:33], off

; DI void st_bf16x4(bf16_t* p, f32x4 v) { u32x2 o; o.x = pk2e(v[0], v[1]); o.y = pk2e(v[2], v[3]); *(u32x2*)p = o; }
; DI void st_tr4(bf16_t* p, size_t stride, f32x4 v) { p[0] = f2bf(v[0]); p[stride] = f2bf(v[1]); p[2 * stride] = f2bf(v[2]); p[3 * stride] = f2bf(v[3]); }
;     ...
;       for (int m = 0; m < 4; ++m) {
;         const int row = brow + ai * HALF + wr * 64 + m * 16 + fr_e;
;         const float rsc = epi.rowscale(row);
;         float ssq = 0.f;
; #pragma unroll
;         for (int bj = 0; bj < 2; ++bj)
;           ssq += epi(row, bcol + bj * HALF + wc * 32, fq_e, acc[ai][bj][m][0] * rsc, acc[ai][bj][m][1] * rsc);
;   DI float rowscale(int row) const { const f32x4 a = *(const f32x4*)(ssp_in + (size_t)row * 8), b = *(const f32x4*)(ssp_in + (size_t)row * 8 + 4);
;     return rsqrtf((((a[0] + a[1]) + (a[2] + a[3])) + ((b[0] + b[1]) + (b[2] + b[3]))) * (1.f / D_) + EPS_); }
;   DI void one(int row, int c, f32x4 v) const {
;     const int b = row >> 12, t = row & 4095;
;     if (c < 3072) {
;       const int seg = c >> 10, cc = c & 1023, h = cc >> 7, d = cc & 127;
;       if (seg < 2) st_bf16x4((bf16_t*)(ws + (seg == 0 ? E_FQ : E_FK)) + ((size_t)(b * 8 + h) * T_ + t) * 128 + d, v);
;       else st_tr4((bf16_t*)(ws + E_FVT) + (size_t)(b * 8 + h) * 128 * T_ + (size_t)(t >> 5) * 4096 + d * 32 + ((((t & 31) >> 2) ^ ((d >> 2) & 7)) << 2) + (t & 3), 32, v);
;     } else if (c < 4096) { st_bf16x4((bf16_t*)(ws + E_HQ) + (size_t)row * 1024 + (c - 3072), v);
;     } else if (c < 5120) { *(f32x4*)((float*)(ws + E_HF) + (size_t)row * 1024 + (c - 4096)) = v;
;     } else if (c < 6144) { const int cc = c - 5120, h = cc >> 7, d = cc & 127; st_tr4((bf16_t*)(ws + E_HIT) + (size_t)(b * 8 + h) * 128 * T_ + (size_t)(t >> 5) * 4096 + d * 32 + (t & 31), 32, v);
;     } else if (c < 7168) { st_bf16x4((bf16_t*)(ws + E_HG) + (size_t)row * 1024 + (c - 6144), v);
;     } else if (c < 7176) { *(f32x4*)((float*)(ws + E_FF) + (size_t)row * 8 + (c - 7168)) = v; }
.LBB0_1708:
	s_or_b64 exec, exec, s[10:11]
	v_or_b32_e32 v28, s18, v95
	v_ashrrev_i32_e32 v29, 31, v28
	v_readlane_b32 s10, v253, 52
	v_lshlrev_b64 v[26:27], 5, v[28:29]
	v_readlane_b32 s11, v253, 53
	s_nop 1
	v_lshl_add_u64 v[22:23], s[10:11], 0, v[26:27]
	s_nop 0
	v_readlane_b32 s10, v253, 48
	v_readlane_b32 s11, v253, 49
	s_waitcnt vmcnt(0)
	v_mov_b32_e32 v30, v232
	v_mov_b32_e32 v31, v236
	v_mov_b32_e32 v236, v233
	v_pk_add_f32 v[232:233], v[30:31], v[236:237]
	v_mov_b32_e32 v236, v234
	v_mov_b32_e32 v237, v238
	v_mov_b32_e32 v238, v235
	v_pk_add_f32 v[234:235], v[236:237], v[238:239]
	s_nop 0
	v_pk_add_f32 v[232:233], v[232:233], v[234:235]
	v_lshl_add_u64 v[20:21], s[10:11], 0, v[26:27]
	v_add_f32_e32 v0, v232, v233
	v_fmamk_f32 v0, v0, 0x3a000000, v249
	v_cmp_gt_f32_e32 vcc, s84, v0
	v_mul_f32_e32 v18, 0x4b800000, v0
	s_movk_i32 s10, 0x7e0
	v_cndmask_b32_e32 v0, v0, v18, vcc
	v_rsq_f32_e32 v0, v0
	v_lshlrev_b64 v[26:27], 11, v[28:29]
	v_mul_f32_e32 v18, 0x45800000, v0
	v_cndmask_b32_e32 v24, v0, v18, vcc
	v_lshlrev_b32_e32 v0, 8, v28
	v_mad_i64_i32 v[18:19], s[10:11], v28, s10, v[20:21]
	v_and_b32_e32 v0, 0xfe000, v0
	v_lshl_add_u64 v[22:23], s[4:5], 0, v[0:1]
	v_lshl_add_u64 v[26:27], v[18:19], 0, v[26:27]
	v_pk_mul_f32 v[16:17], v[16:17], v[24:25] op_sel_hi:[1,0]
	v_pk_mul_f32 v[14:15], v[14:15], v[24:25] op_sel_hi:[1,0]
	s_and_saveexec_b64 s[10:11], s[40:41]
	s_xor_b64 s[10:11], exec, s[10:11]
	s_cbranch_execz .LBB0_1727
	s_cmpk_lt_u32 s8, 0x1000
	s_mov_b64 s[12:13], -1
	s_cbranch_scc1 .LBB0_1725
	s_cmpk_lt_u32 s8, 0x1400
	s_cbranch_scc1 .LBB0_1722
	s_cmpk_lt_u32 s8, 0x1800
	s_cbranch_scc1 .LBB0_1719
	s_cmpk_lt_u32 s8, 0x1c00
	s_cbranch_scc1 .LBB0_1716
	s_movk_i32 s12, 0x1c08
	v_cmp_gt_u32_e32 vcc, s12, v134
	s_and_saveexec_b64 s[12:13], vcc
	s_cbranch_execz .LBB0_1715
	v_mov_b32_e32 v135, v1
	v_lshl_add_u64 v[30:31], v[134:135], 2, v[20:21]
	v_add_co_u32_e32 v30, vcc, 0x3513e000, v30
	s_nop 1
	v_addc_co_u32_e32 v31, vcc, 0, v31, vcc
	global_store_dwordx4 v[30:31], v[14:17], off
